# added: mLSTM fwd/bwd loops software-pipelined LDS reads (QK double buffer, PV second buffer); ss-load hoist in kv-up and layer1 in-proj epilogues
# speedup vs baseline: 1.0017x; 1.0017x over previous
; __device__ __forceinline__ u32x4 pack8(const f32x4 a, const f32x4 b) { u32x4 w; w.x = cvt_pk_bf16(a[0], a[1]); w.y = cvt_pk_bf16(a[2], a[3]); w.z = cvt_pk_bf16(b[0], b[1]); w.w = cvt_pk_bf16(b[2], b[3]); return w; }
; __device__ __forceinline__ float rstd_of(ssq_t ss, float inv_n) { return __builtin_amdgcn_rsqf((float)ss * (1.0f / 16777216.0f) * inv_n + 1e-6f); }
;     __device__ __forceinline__ void operator()(const f32x4 (&acc)[2][2][4][2], const Unit& u, int wr, int wc, int fr, int fq) const {
;         const int row0 = u.pm * BM + wr * 64 + fr;
; #pragma unroll
;         for (int ai = 0; ai < 2; ++ai)
; #pragma unroll
;             for (int m = 0; m < 4; ++m) { const int row = row0 + ai * HALF + m * 16; const float rs = rstd_of(ss_ckv[row], 1.0f / 512.0f);
;                 *(u32x4*)(KF + (size_t)row * 1536 + u.pn * 192 + wc * 32 + 8 * fq) = pack8(acc[ai][0][m][0] * rs, acc[ai][0][m][1] * rs);
;                 *(u32x4*)(V + (size_t)row * 1024 + u.pn * 128 + wc * 32 + 8 * fq) = pack8(acc[ai][1][m][0] * rs, acc[ai][1][m][1] * rs); }
;     }
.LBB0_841:
	v_lshl_add_u32 v146, s0, 8, v150
	v_ashrrev_i32_e32 v147, 31, v146
	v_lshl_add_u64 v[148:149], v[146:147], 3, s[62:63]
	global_load_dwordx2 v[156:157], v[148:149], off
	global_load_dwordx2 v[170:171], v[148:149], off offset:128
	global_load_dwordx2 v[172:173], v[148:149], off offset:256
	global_load_dwordx2 v[174:175], v[148:149], off offset:384
	global_load_dwordx2 v[176:177], v[148:149], off offset:1024
	global_load_dwordx2 v[178:179], v[148:149], off offset:1152
	global_load_dwordx2 v[180:181], v[148:149], off offset:1280
	global_load_dwordx2 v[182:183], v[148:149], off offset:1408
	s_mul_i32 s0, s92, 0xc0
	s_ashr_i32 s1, s0, 31
	s_lshl_b64 s[0:1], s[0:1], 1
	s_lshl_b32 s18, s92, 7
	s_ashr_i32 s19, s18, 31
	s_lshl_b64 s[18:19], s[18:19], 1
	s_andn2_b64 vcc, exec, s[2:3]
	s_waitcnt vmcnt(0)
	v_ffbh_u32_e32 v158, v157
	v_min_u32_e32 v158, 32, v158
	v_lshlrev_b64 v[156:157], v158, v[156:157]
	v_min_u32_e32 v156, 1, v156
	v_or_b32_e32 v156, v157, v156
	v_cvt_f32_u32_e32 v156, v156
	v_sub_u32_e32 v157, 32, v158
	v_ldexp_f32 v156, v156, v157
	v_mul_f32_e32 v156, 0x33800000, v156
	v_fmamk_f32 v156, v156, 0x3b000000, v155
	v_rsq_f32_e32 v156, v156
	s_nop 0
	v_pk_mul_f32 v[124:125], v[124:125], v[156:157] op_sel_hi:[1,0]
	v_pk_mul_f32 v[120:121], v[120:121], v[156:157] op_sel_hi:[1,0]
	v_pk_mul_f32 v[126:127], v[126:127], v[156:157] op_sel_hi:[1,0]
	v_pk_mul_f32 v[158:159], v[122:123], v[156:157] op_sel_hi:[1,0]
	v_cvt_pk_bf16_f32 v122, v124, v125
	v_cvt_pk_bf16_f32 v124, v120, v121
	v_mov_b64_e32 v[120:121], s[52:53]
	v_cvt_pk_bf16_f32 v123, v126, v127
	v_mad_i64_i32 v[126:127], s[36:37], v146, s90, v[120:121]
	v_lshl_add_u64 v[126:127], v[126:127], 0, s[0:1]
	v_lshl_add_u64 v[126:127], v[126:127], 0, s[4:5]
	v_cvt_pk_bf16_f32 v125, v158, v159
	v_lshl_add_u64 v[126:127], v[126:127], 0, v[144:145]
	v_pk_mul_f32 v[116:117], v[116:117], v[156:157] op_sel_hi:[1,0]
	global_store_dwordx4 v[126:127], v[122:125], off
	v_pk_mul_f32 v[118:119], v[118:119], v[156:157] op_sel_hi:[1,0]
	s_nop 0
	v_pk_mul_f32 v[122:123], v[114:115], v[156:157] op_sel_hi:[1,0]
	v_pk_mul_f32 v[114:115], v[112:113], v[156:157] op_sel_hi:[1,0]
	v_cvt_pk_bf16_f32 v112, v116, v117
	v_lshlrev_b64 v[116:117], 11, v[146:147]
	v_lshl_add_u64 v[116:117], s[58:59], 0, v[116:117]
	v_lshl_add_u64 v[116:117], v[116:117], 0, s[18:19]
	v_lshl_add_u64 v[116:117], v[116:117], 0, s[4:5]
	v_cvt_pk_bf16_f32 v113, v118, v119
	v_cvt_pk_bf16_f32 v114, v114, v115
	v_cvt_pk_bf16_f32 v115, v122, v123
	v_lshl_add_u64 v[116:117], v[116:117], 0, v[144:145]
	global_store_dwordx4 v[116:117], v[112:115], off
	s_nop 1
	v_or_b32_e32 v112, 16, v146
	v_ashrrev_i32_e32 v113, 31, v112
	v_lshl_add_u64 v[114:115], v[112:113], 3, s[62:63]
	s_nop 1
	v_ffbh_u32_e32 v116, v171
	v_min_u32_e32 v116, 32, v116
	v_lshlrev_b64 v[114:115], v116, v[170:171]
	v_min_u32_e32 v114, 1, v114
	v_or_b32_e32 v114, v115, v114
	v_cvt_f32_u32_e32 v114, v114
	v_sub_u32_e32 v115, 32, v116
	v_ldexp_f32 v114, v114, v115
	v_mul_f32_e32 v114, 0x33800000, v114
	v_fmamk_f32 v114, v114, 0x3b000000, v155
	v_rsq_f32_e32 v114, v114
	s_nop 0
	v_pk_mul_f32 v[108:109], v[108:109], v[114:115] op_sel_hi:[1,0]
	v_pk_mul_f32 v[116:117], v[106:107], v[114:115] op_sel_hi:[1,0]
	v_pk_mul_f32 v[106:107], v[104:105], v[114:115] op_sel_hi:[1,0]
	v_cvt_pk_bf16_f32 v104, v108, v109
	v_mad_i64_i32 v[108:109], s[36:37], v112, s90, v[120:121]
	v_lshl_add_u64 v[108:109], v[108:109], 0, s[0:1]
	v_pk_mul_f32 v[110:111], v[110:111], v[114:115] op_sel_hi:[1,0]
	v_lshl_add_u64 v[108:109], v[108:109], 0, s[4:5]
	v_cvt_pk_bf16_f32 v105, v110, v111
	v_cvt_pk_bf16_f32 v106, v106, v107
	v_cvt_pk_bf16_f32 v107, v116, v117
	v_lshl_add_u64 v[108:109], v[108:109], 0, v[144:145]
	v_pk_mul_f32 v[100:101], v[100:101], v[114:115] op_sel_hi:[1,0]
	global_store_dwordx4 v[108:109], v[104:107], off
	v_pk_mul_f32 v[102:103], v[102:103], v[114:115] op_sel_hi:[1,0]
	s_nop 0
	v_pk_mul_f32 v[104:105], v[98:99], v[114:115] op_sel_hi:[1,0]
	v_pk_mul_f32 v[98:99], v[96:97], v[114:115] op_sel_hi:[1,0]
	v_cvt_pk_bf16_f32 v96, v100, v101
	v_lshlrev_b64 v[100:101], 11, v[112:113]
	v_lshl_add_u64 v[100:101], s[58:59], 0, v[100:101]
	v_lshl_add_u64 v[100:101], v[100:101], 0, s[18:19]
	v_lshl_add_u64 v[100:101], v[100:101], 0, s[4:5]
	v_cvt_pk_bf16_f32 v97, v102, v103
	v_cvt_pk_bf16_f32 v98, v98, v99
	v_cvt_pk_bf16_f32 v99, v104, v105
	v_lshl_add_u64 v[100:101], v[100:101], 0, v[144:145]
	global_store_dwordx4 v[100:101], v[96:99], off
	s_nop 1
	v_or_b32_e32 v96, 32, v146
	v_ashrrev_i32_e32 v97, 31, v96
	v_lshl_add_u64 v[98:99], v[96:97], 3, s[62:63]
	s_nop 1
	v_ffbh_u32_e32 v100, v173
	v_min_u32_e32 v100, 32, v100
	v_lshlrev_b64 v[98:99], v100, v[172:173]
	v_min_u32_e32 v98, 1, v98
	v_or_b32_e32 v98, v99, v98
	v_cvt_f32_u32_e32 v98, v98
	v_sub_u32_e32 v99, 32, v100
	v_ldexp_f32 v98, v98, v99
	v_mul_f32_e32 v98, 0x33800000, v98
	v_fmamk_f32 v98, v98, 0x3b000000, v155
	v_rsq_f32_e32 v98, v98
	s_nop 0
	v_pk_mul_f32 v[92:93], v[92:93], v[98:99] op_sel_hi:[1,0]
	v_pk_mul_f32 v[100:101], v[90:91], v[98:99] op_sel_hi:[1,0]
	v_pk_mul_f32 v[90:91], v[88:89], v[98:99] op_sel_hi:[1,0]
	v_cvt_pk_bf16_f32 v88, v92, v93
	v_mad_i64_i32 v[92:93], s[36:37], v96, s90, v[120:121]
	v_lshl_add_u64 v[92:93], v[92:93], 0, s[0:1]
	v_pk_mul_f32 v[94:95], v[94:95], v[98:99] op_sel_hi:[1,0]
	v_lshl_add_u64 v[92:93], v[92:93], 0, s[4:5]
	v_cvt_pk_bf16_f32 v89, v94, v95
	v_cvt_pk_bf16_f32 v90, v90, v91
	v_cvt_pk_bf16_f32 v91, v100, v101
	v_lshl_add_u64 v[92:93], v[92:93], 0, v[144:145]
	v_pk_mul_f32 v[84:85], v[84:85], v[98:99] op_sel_hi:[1,0]
	global_store_dwordx4 v[92:93], v[88:91], off
; __device__ __forceinline__ u32x4 pack8(const f32x4 a, const f32x4 b) { u32x4 w; w.x = cvt_pk_bf16(a[0], a[1]); w.y = cvt_pk_bf16(a[2], a[3]); w.z = cvt_pk_bf16(b[0], b[1]); w.w = cvt_pk_bf16(b[2], b[3]); return w; }
; __device__ __forceinline__ float rstd_of(ssq_t ss, float inv_n) { return __builtin_amdgcn_rsqf((float)ss * (1.0f / 16777216.0f) * inv_n + 1e-6f); }
;     __device__ __forceinline__ void operator()(const f32x4 (&acc)[2][2][4][2], const Unit& u, int wr, int wc, int fr, int fq) const {
;         const int row0 = u.pm * BM + wr * 64 + fr;
; #pragma unroll
;         for (int ai = 0; ai < 2; ++ai)
; #pragma unroll
;             for (int m = 0; m < 4; ++m) { const int row = row0 + ai * HALF + m * 16; const float rs = rstd_of(ss_ckv[row], 1.0f / 512.0f);
;                 *(u32x4*)(KF + (size_t)row * 1536 + u.pn * 192 + wc * 32 + 8 * fq) = pack8(acc[ai][0][m][0] * rs, acc[ai][0][m][1] * rs);
;                 *(u32x4*)(V + (size_t)row * 1024 + u.pn * 128 + wc * 32 + 8 * fq) = pack8(acc[ai][1][m][0] * rs, acc[ai][1][m][1] * rs); }
;     }
	v_pk_mul_f32 v[86:87], v[86:87], v[98:99] op_sel_hi:[1,0]
	s_nop 0
	v_pk_mul_f32 v[88:89], v[82:83], v[98:99] op_sel_hi:[1,0]
	v_pk_mul_f32 v[82:83], v[80:81], v[98:99] op_sel_hi:[1,0]
	v_cvt_pk_bf16_f32 v80, v84, v85
	v_lshlrev_b64 v[84:85], 11, v[96:97]
	v_lshl_add_u64 v[84:85], s[58:59], 0, v[84:85]
	v_lshl_add_u64 v[84:85], v[84:85], 0, s[18:19]
	v_lshl_add_u64 v[84:85], v[84:85], 0, s[4:5]
	v_cvt_pk_bf16_f32 v81, v86, v87
	v_cvt_pk_bf16_f32 v82, v82, v83
	v_cvt_pk_bf16_f32 v83, v88, v89
	v_lshl_add_u64 v[84:85], v[84:85], 0, v[144:145]
	global_store_dwordx4 v[84:85], v[80:83], off
	s_nop 1
	v_or_b32_e32 v80, 48, v146
	v_ashrrev_i32_e32 v81, 31, v80
	v_lshl_add_u64 v[82:83], v[80:81], 3, s[62:63]
	s_nop 1
	v_ffbh_u32_e32 v84, v175
	v_min_u32_e32 v84, 32, v84
	v_lshlrev_b64 v[82:83], v84, v[174:175]
	v_min_u32_e32 v82, 1, v82
	v_or_b32_e32 v82, v83, v82
	v_cvt_f32_u32_e32 v82, v82
	v_sub_u32_e32 v83, 32, v84
	v_ldexp_f32 v82, v82, v83
	v_mul_f32_e32 v82, 0x33800000, v82
	v_fmamk_f32 v82, v82, 0x3b000000, v155
	v_rsq_f32_e32 v82, v82
	s_nop 0
	v_pk_mul_f32 v[76:77], v[76:77], v[82:83] op_sel_hi:[1,0]
	v_pk_mul_f32 v[84:85], v[74:75], v[82:83] op_sel_hi:[1,0]
	v_pk_mul_f32 v[74:75], v[72:73], v[82:83] op_sel_hi:[1,0]
	v_cvt_pk_bf16_f32 v72, v76, v77
	v_mad_i64_i32 v[76:77], s[36:37], v80, s90, v[120:121]
	v_lshl_add_u64 v[76:77], v[76:77], 0, s[0:1]
	v_pk_mul_f32 v[78:79], v[78:79], v[82:83] op_sel_hi:[1,0]
	v_lshl_add_u64 v[76:77], v[76:77], 0, s[4:5]
	v_cvt_pk_bf16_f32 v73, v78, v79
	v_cvt_pk_bf16_f32 v74, v74, v75
	v_cvt_pk_bf16_f32 v75, v84, v85
	v_lshl_add_u64 v[76:77], v[76:77], 0, v[144:145]
	v_pk_mul_f32 v[68:69], v[68:69], v[82:83] op_sel_hi:[1,0]
	global_store_dwordx4 v[76:77], v[72:75], off
	v_pk_mul_f32 v[70:71], v[70:71], v[82:83] op_sel_hi:[1,0]
	s_nop 0
	v_pk_mul_f32 v[72:73], v[66:67], v[82:83] op_sel_hi:[1,0]
	v_pk_mul_f32 v[66:67], v[64:65], v[82:83] op_sel_hi:[1,0]
	v_cvt_pk_bf16_f32 v64, v68, v69
	v_lshlrev_b64 v[68:69], 11, v[80:81]
	v_lshl_add_u64 v[68:69], s[58:59], 0, v[68:69]
	v_lshl_add_u64 v[68:69], v[68:69], 0, s[18:19]
	v_lshl_add_u64 v[68:69], v[68:69], 0, s[4:5]
	v_cvt_pk_bf16_f32 v65, v70, v71
	v_cvt_pk_bf16_f32 v66, v66, v67
	v_cvt_pk_bf16_f32 v67, v72, v73
	v_lshl_add_u64 v[68:69], v[68:69], 0, v[144:145]
	global_store_dwordx4 v[68:69], v[64:67], off
	s_nop 1
	v_ffbh_u32_e32 v68, v177
	v_min_u32_e32 v68, 32, v68
	v_lshlrev_b64 v[66:67], v68, v[176:177]
	v_min_u32_e32 v66, 1, v66
	v_or_b32_e32 v66, v67, v66
	v_cvt_f32_u32_e32 v66, v66
	v_sub_u32_e32 v67, 32, v68
	v_add_u32_e32 v64, 0x80, v146
	v_ashrrev_i32_e32 v65, 31, v64
	v_ldexp_f32 v66, v66, v67
	v_mul_f32_e32 v66, 0x33800000, v66
	v_fmamk_f32 v66, v66, 0x3b000000, v155
	v_rsq_f32_e32 v66, v66
	s_nop 0
	v_pk_mul_f32 v[60:61], v[60:61], v[66:67] op_sel_hi:[1,0]
	v_pk_mul_f32 v[68:69], v[58:59], v[66:67] op_sel_hi:[1,0]
	v_pk_mul_f32 v[58:59], v[56:57], v[66:67] op_sel_hi:[1,0]
	v_cvt_pk_bf16_f32 v56, v60, v61
	v_mad_i64_i32 v[60:61], s[36:37], v64, s90, v[120:121]
	v_lshl_add_u64 v[60:61], v[60:61], 0, s[0:1]
	v_pk_mul_f32 v[62:63], v[62:63], v[66:67] op_sel_hi:[1,0]
	v_lshl_add_u64 v[60:61], v[60:61], 0, s[4:5]
	v_cvt_pk_bf16_f32 v57, v62, v63
	v_cvt_pk_bf16_f32 v58, v58, v59
	v_cvt_pk_bf16_f32 v59, v68, v69
	v_lshl_add_u64 v[60:61], v[60:61], 0, v[144:145]
	v_pk_mul_f32 v[52:53], v[52:53], v[66:67] op_sel_hi:[1,0]
	global_store_dwordx4 v[60:61], v[56:59], off
	v_pk_mul_f32 v[54:55], v[54:55], v[66:67] op_sel_hi:[1,0]
	s_nop 0
	v_pk_mul_f32 v[56:57], v[50:51], v[66:67] op_sel_hi:[1,0]
	v_pk_mul_f32 v[50:51], v[48:49], v[66:67] op_sel_hi:[1,0]
	v_cvt_pk_bf16_f32 v48, v52, v53
	v_lshlrev_b64 v[52:53], 11, v[64:65]
	v_lshl_add_u64 v[52:53], s[58:59], 0, v[52:53]
	v_lshl_add_u64 v[52:53], v[52:53], 0, s[18:19]
	v_lshl_add_u64 v[52:53], v[52:53], 0, s[4:5]
	v_cvt_pk_bf16_f32 v49, v54, v55
	v_cvt_pk_bf16_f32 v50, v50, v51
	v_cvt_pk_bf16_f32 v51, v56, v57
	v_lshl_add_u64 v[52:53], v[52:53], 0, v[144:145]
	global_store_dwordx4 v[52:53], v[48:51], off
	s_nop 1
	v_ffbh_u32_e32 v52, v179
	v_min_u32_e32 v52, 32, v52
	v_lshlrev_b64 v[50:51], v52, v[178:179]
	v_min_u32_e32 v50, 1, v50
	v_or_b32_e32 v50, v51, v50
	v_cvt_f32_u32_e32 v50, v50
	v_sub_u32_e32 v51, 32, v52
	v_add_u32_e32 v48, 0x90, v146
	v_ashrrev_i32_e32 v49, 31, v48
	v_ldexp_f32 v50, v50, v51
	v_mul_f32_e32 v50, 0x33800000, v50
	v_fmamk_f32 v50, v50, 0x3b000000, v155
	v_rsq_f32_e32 v50, v50
	s_nop 0
	v_pk_mul_f32 v[44:45], v[44:45], v[50:51] op_sel_hi:[1,0]
	v_pk_mul_f32 v[52:53], v[42:43], v[50:51] op_sel_hi:[1,0]
; __device__ __forceinline__ u32x4 pack8(const f32x4 a, const f32x4 b) { u32x4 w; w.x = cvt_pk_bf16(a[0], a[1]); w.y = cvt_pk_bf16(a[2], a[3]); w.z = cvt_pk_bf16(b[0], b[1]); w.w = cvt_pk_bf16(b[2], b[3]); return w; }
; __device__ __forceinline__ float rstd_of(ssq_t ss, float inv_n) { return __builtin_amdgcn_rsqf((float)ss * (1.0f / 16777216.0f) * inv_n + 1e-6f); }
;     __device__ __forceinline__ void operator()(const f32x4 (&acc)[2][2][4][2], const Unit& u, int wr, int wc, int fr, int fq) const {
;         const int row0 = u.pm * BM + wr * 64 + fr;
; #pragma unroll
;         for (int ai = 0; ai < 2; ++ai)
; #pragma unroll
;             for (int m = 0; m < 4; ++m) { const int row = row0 + ai * HALF + m * 16; const float rs = rstd_of(ss_ckv[row], 1.0f / 512.0f);
;                 *(u32x4*)(KF + (size_t)row * 1536 + u.pn * 192 + wc * 32 + 8 * fq) = pack8(acc[ai][0][m][0] * rs, acc[ai][0][m][1] * rs);
;                 *(u32x4*)(V + (size_t)row * 1024 + u.pn * 128 + wc * 32 + 8 * fq) = pack8(acc[ai][1][m][0] * rs, acc[ai][1][m][1] * rs); }
;     }
	v_pk_mul_f32 v[42:43], v[40:41], v[50:51] op_sel_hi:[1,0]
	v_cvt_pk_bf16_f32 v40, v44, v45
	v_mad_i64_i32 v[44:45], s[36:37], v48, s90, v[120:121]
	v_lshl_add_u64 v[44:45], v[44:45], 0, s[0:1]
	v_pk_mul_f32 v[46:47], v[46:47], v[50:51] op_sel_hi:[1,0]
	v_lshl_add_u64 v[44:45], v[44:45], 0, s[4:5]
	v_cvt_pk_bf16_f32 v41, v46, v47
	v_cvt_pk_bf16_f32 v42, v42, v43
	v_cvt_pk_bf16_f32 v43, v52, v53
	v_lshl_add_u64 v[44:45], v[44:45], 0, v[144:145]
	v_pk_mul_f32 v[36:37], v[36:37], v[50:51] op_sel_hi:[1,0]
	global_store_dwordx4 v[44:45], v[40:43], off
	v_pk_mul_f32 v[38:39], v[38:39], v[50:51] op_sel_hi:[1,0]
	s_nop 0
	v_pk_mul_f32 v[40:41], v[34:35], v[50:51] op_sel_hi:[1,0]
	v_pk_mul_f32 v[34:35], v[32:33], v[50:51] op_sel_hi:[1,0]
	v_cvt_pk_bf16_f32 v32, v36, v37
	v_lshlrev_b64 v[36:37], 11, v[48:49]
	v_lshl_add_u64 v[36:37], s[58:59], 0, v[36:37]
	v_lshl_add_u64 v[36:37], v[36:37], 0, s[18:19]
	v_lshl_add_u64 v[36:37], v[36:37], 0, s[4:5]
	v_cvt_pk_bf16_f32 v33, v38, v39
	v_cvt_pk_bf16_f32 v34, v34, v35
	v_cvt_pk_bf16_f32 v35, v40, v41
	v_lshl_add_u64 v[36:37], v[36:37], 0, v[144:145]
	global_store_dwordx4 v[36:37], v[32:35], off
	s_nop 1
	v_ffbh_u32_e32 v36, v181
	v_min_u32_e32 v36, 32, v36
	v_lshlrev_b64 v[34:35], v36, v[180:181]
	v_min_u32_e32 v34, 1, v34
	v_or_b32_e32 v34, v35, v34
	v_cvt_f32_u32_e32 v34, v34
	v_sub_u32_e32 v35, 32, v36
	v_add_u32_e32 v32, 0xa0, v146
	v_ashrrev_i32_e32 v33, 31, v32
	v_ldexp_f32 v34, v34, v35
	v_mul_f32_e32 v34, 0x33800000, v34
	v_fmamk_f32 v34, v34, 0x3b000000, v155
	v_rsq_f32_e32 v34, v34
	s_nop 0
	v_pk_mul_f32 v[28:29], v[28:29], v[34:35] op_sel_hi:[1,0]
	v_pk_mul_f32 v[36:37], v[26:27], v[34:35] op_sel_hi:[1,0]
	v_pk_mul_f32 v[26:27], v[24:25], v[34:35] op_sel_hi:[1,0]
	v_cvt_pk_bf16_f32 v24, v28, v29
	v_mad_i64_i32 v[28:29], s[36:37], v32, s90, v[120:121]
	v_lshl_add_u64 v[28:29], v[28:29], 0, s[0:1]
	v_pk_mul_f32 v[30:31], v[30:31], v[34:35] op_sel_hi:[1,0]
	v_lshl_add_u64 v[28:29], v[28:29], 0, s[4:5]
	v_cvt_pk_bf16_f32 v25, v30, v31
	v_cvt_pk_bf16_f32 v26, v26, v27
	v_cvt_pk_bf16_f32 v27, v36, v37
	v_lshl_add_u64 v[28:29], v[28:29], 0, v[144:145]
	v_pk_mul_f32 v[20:21], v[20:21], v[34:35] op_sel_hi:[1,0]
	global_store_dwordx4 v[28:29], v[24:27], off
	v_pk_mul_f32 v[22:23], v[22:23], v[34:35] op_sel_hi:[1,0]
	s_nop 0
	v_pk_mul_f32 v[24:25], v[18:19], v[34:35] op_sel_hi:[1,0]
	v_pk_mul_f32 v[18:19], v[16:17], v[34:35] op_sel_hi:[1,0]
	v_cvt_pk_bf16_f32 v16, v20, v21
	v_lshlrev_b64 v[20:21], 11, v[32:33]
	v_lshl_add_u64 v[20:21], s[58:59], 0, v[20:21]
	v_lshl_add_u64 v[20:21], v[20:21], 0, s[18:19]
	v_lshl_add_u64 v[20:21], v[20:21], 0, s[4:5]
	v_cvt_pk_bf16_f32 v17, v22, v23
	v_cvt_pk_bf16_f32 v18, v18, v19
	v_cvt_pk_bf16_f32 v19, v24, v25
	v_lshl_add_u64 v[20:21], v[20:21], 0, v[144:145]
	global_store_dwordx4 v[20:21], v[16:19], off
	s_nop 1
	v_ffbh_u32_e32 v20, v183
	v_min_u32_e32 v20, 32, v20
	v_lshlrev_b64 v[18:19], v20, v[182:183]
	v_min_u32_e32 v18, 1, v18
	v_or_b32_e32 v18, v19, v18
	v_cvt_f32_u32_e32 v18, v18
	v_sub_u32_e32 v19, 32, v20
	v_add_u32_e32 v16, 0xb0, v146
	v_ashrrev_i32_e32 v17, 31, v16
	v_ldexp_f32 v18, v18, v19
	v_mul_f32_e32 v18, 0x33800000, v18
	v_fmamk_f32 v18, v18, 0x3b000000, v155
	v_rsq_f32_e32 v18, v18
	s_nop 0
	v_pk_mul_f32 v[12:13], v[12:13], v[18:19] op_sel_hi:[1,0]
	v_pk_mul_f32 v[20:21], v[10:11], v[18:19] op_sel_hi:[1,0]
	v_pk_mul_f32 v[10:11], v[8:9], v[18:19] op_sel_hi:[1,0]
	v_cvt_pk_bf16_f32 v8, v12, v13
	v_mad_i64_i32 v[12:13], s[36:37], v16, s90, v[120:121]
	v_lshl_add_u64 v[12:13], v[12:13], 0, s[0:1]
	v_pk_mul_f32 v[14:15], v[14:15], v[18:19] op_sel_hi:[1,0]
	v_lshl_add_u64 v[12:13], v[12:13], 0, s[4:5]
	v_cvt_pk_bf16_f32 v9, v14, v15
	v_cvt_pk_bf16_f32 v10, v10, v11
	v_cvt_pk_bf16_f32 v11, v20, v21
	v_lshl_add_u64 v[12:13], v[12:13], 0, v[144:145]
	v_pk_mul_f32 v[4:5], v[4:5], v[18:19] op_sel_hi:[1,0]
	global_store_dwordx4 v[12:13], v[8:11], off
	v_pk_mul_f32 v[6:7], v[6:7], v[18:19] op_sel_hi:[1,0]
	s_mov_b64 s[0:1], -1
	v_pk_mul_f32 v[8:9], v[2:3], v[18:19] op_sel_hi:[1,0]
	v_pk_mul_f32 v[2:3], v[0:1], v[18:19] op_sel_hi:[1,0]
	v_cvt_pk_bf16_f32 v0, v4, v5
	v_lshlrev_b64 v[4:5], 11, v[16:17]
	v_lshl_add_u64 v[4:5], s[58:59], 0, v[4:5]
	v_lshl_add_u64 v[4:5], v[4:5], 0, s[18:19]
	v_lshl_add_u64 v[4:5], v[4:5], 0, s[4:5]
	v_cvt_pk_bf16_f32 v1, v6, v7
	v_cvt_pk_bf16_f32 v2, v2, v3
	v_cvt_pk_bf16_f32 v3, v8, v9
	v_lshl_add_u64 v[4:5], v[4:5], 0, v[144:145]
	global_store_dwordx4 v[4:5], v[0:3], off
	s_cbranch_vccnz .LBB0_830
	s_andn2_b64 vcc, exec, s[60:61]
	s_cbranch_vccnz .LBB0_829
	s_barrier
	s_branch .LBB0_829

; #define SBAR() __builtin_amdgcn_sched_barrier(0)
; template <int OFF> __device__ __forceinline__ s16x4 tr_read(int vb) { s16x4 r; asm volatile("ds_read_b64_tr_b16 %0, %1 offset:%2" : "=&v"(r) : "v"(vb), "i"(OFF) : "memory"); return r; }
; __device__ __forceinline__ void finishW(f32x16& p0, f32x16& p1, float& l_reg, bf16x8& pa0, bf16x8& pa1, bf16x8& pa2, bf16x8& pa3) {
;   float ps = 0;
; #pragma unroll
;   for (int r = 0; r < 16; ++r) ps += p0[r];
; #pragma unroll
;   for (int r = 0; r < 16; ++r) ps += p1[r];
;   { auto rr = __builtin_amdgcn_permlane32_swap(__float_as_uint(ps), __float_as_uint(ps), false, false);
;     ps = __uint_as_float(rr[0]) + __uint_as_float(rr[1]); }
;   l_reg += ps;
;   PK4(p0, 0, pa0); PK4(p0, 8, pa1); PK4(p1, 0, pa2); PK4(p1, 8, pa3);
; }
; template <int D0> __device__ __forceinline__ void pv_one_lean(f32x16& od, int vb, bf16x8 pa0, bf16x8 pa1, bf16x8 pa2, bf16x8 pa3) {
;     ...
;   { const s16x4 l0 = tr_read<v_rd_off(D0, 0, 0)>(vb), h0 = tr_read<v_rd_off(D0, 0, 1)>(vb), l1 = tr_read<v_rd_off(D0, 1, 0)>(vb), h1 = tr_read<v_rd_off(D0, 1, 1)>(vb);
;     asm volatile("s_waitcnt lgkmcnt(0)" ::: "memory"); SBAR();
;     od = __builtin_amdgcn_mfma_f32_32x32x16_bf16(pa0, PKL(l0, h0), od, 0, 0, 0); od = __builtin_amdgcn_mfma_f32_32x32x16_bf16(pa1, PKL(l1, h1), od, 0, 0, 0); }
;   SBAR();
;   { const s16x4 l2 = tr_read<v_rd_off(D0, 2, 0)>(vb), h2 = tr_read<v_rd_off(D0, 2, 1)>(vb), l3 = tr_read<v_rd_off(D0, 3, 0)>(vb), h3 = tr_read<v_rd_off(D0, 3, 1)>(vb);
;     asm volatile("s_waitcnt lgkmcnt(0)" ::: "memory"); SBAR();
;     od = __builtin_amdgcn_mfma_f32_32x32x16_bf16(pa2, PKL(l2, h2), od, 0, 0, 0); od = __builtin_amdgcn_mfma_f32_32x32x16_bf16(pa3, PKL(l3, h3), od, 0, 0, 0); }
;     ...
; }
; __device__ __forceinline__ void pv_d0_lean(f32x16* o, int vb, bf16x8 pa0, bf16x8 pa1, bf16x8 pa2, bf16x8 pa3) {
;   pv_one_lean<0>(o[0], vb, pa0, pa1, pa2, pa3); SBAR(); pv_one_lean<1>(o[1], vb, pa0, pa1, pa2, pa3); SBAR(); pv_one_lean<2>(o[2], vb, pa0, pa1, pa2, pa3); SBAR(); pv_one_lean<3>(o[3], vb, pa0, pa1, pa2, pa3);
; }
.LBB0_1040:
	v_add_f32_e32 v136, 0, v196
	v_add_f32_e32 v136, v197, v136
	v_add_f32_e32 v136, v144, v136
	v_add_f32_e32 v136, v145, v136
	v_add_f32_e32 v136, v198, v136
	v_add_f32_e32 v136, v199, v136
	v_add_f32_e32 v136, v200, v136
	v_add_f32_e32 v136, v201, v136
	v_add_f32_e32 v136, v150, v136
	v_add_f32_e32 v136, v151, v136
	v_add_f32_e32 v136, v152, v136
	v_add_f32_e32 v136, v153, v136
	v_add_f32_e32 v136, v202, v136
	v_add_f32_e32 v136, v203, v136
	v_add_f32_e32 v136, v204, v136
	v_add_f32_e32 v136, v205, v136
	v_add_f32_e32 v136, v128, v136
	v_add_f32_e32 v136, v129, v136
	v_add_f32_e32 v136, v130, v136
	v_add_f32_e32 v136, v131, v136
	v_add_f32_e32 v136, v132, v136
	v_add_f32_e32 v136, v133, v136
	v_add_f32_e32 v136, v134, v136
	v_add_f32_e32 v136, v135, v136
	v_add_f32_e32 v136, v146, v136
	v_add_f32_e32 v136, v147, v136
	v_add_f32_e32 v136, v148, v136
	v_add_f32_e32 v136, v149, v136
	v_add_f32_e32 v136, v154, v136
	v_add_f32_e32 v136, v155, v136
	v_add_f32_e32 v136, v156, v136
	v_add_f32_e32 v136, v157, v136
	v_mov_b32_e32 v137, v136
	s_nop 1
	v_permlane32_swap_b32_e32 v136, v137
	v_add_f32_e32 v136, v136, v137
	v_add_f32_e32 v214, v214, v136
	v_cvt_pk_bf16_f32 v136, v196, v197
	v_cvt_pk_bf16_f32 v137, v144, v145
	v_cvt_pk_bf16_f32 v138, v198, v199
	v_cvt_pk_bf16_f32 v139, v200, v201
	v_cvt_pk_bf16_f32 v140, v150, v151
	v_cvt_pk_bf16_f32 v141, v152, v153
	v_cvt_pk_bf16_f32 v142, v202, v203
	v_cvt_pk_bf16_f32 v143, v204, v205
	v_cvt_pk_bf16_f32 v128, v128, v129
	v_cvt_pk_bf16_f32 v129, v130, v131
	v_cvt_pk_bf16_f32 v130, v132, v133
	v_cvt_pk_bf16_f32 v131, v134, v135
	v_cvt_pk_bf16_f32 v132, v146, v147
	v_cvt_pk_bf16_f32 v133, v148, v149
	v_cvt_pk_bf16_f32 v134, v154, v155
	v_cvt_pk_bf16_f32 v135, v156, v157
	v_permlane32_swap_b32_e32 v136, v138
	v_permlane32_swap_b32_e32 v137, v139
	v_permlane32_swap_b32_e32 v140, v142
	v_permlane32_swap_b32_e32 v141, v143
	v_permlane32_swap_b32_e32 v128, v130
	v_permlane32_swap_b32_e32 v129, v131
	v_permlane32_swap_b32_e32 v132, v134
	v_permlane32_swap_b32_e32 v133, v135
	v_lshl_add_u32 v152, s87, 15, v221
	ds_read_b64_tr_b16 v[144:145], v152 offset:0
	ds_read_b64_tr_b16 v[146:147], v152 offset:0x800
	ds_read_b64_tr_b16 v[148:149], v152 offset:0x1000
	ds_read_b64_tr_b16 v[150:151], v152 offset:0x1800
	ds_read_b64_tr_b16 v[228:229], v152 offset:0x2000
	ds_read_b64_tr_b16 v[230:231], v152 offset:0x2800
	ds_read_b64_tr_b16 v[232:233], v152 offset:0x3000
	ds_read_b64_tr_b16 v[234:235], v152 offset:0x3800
	s_waitcnt lgkmcnt(4)
	v_mfma_f32_32x32x16_bf16 v[112:127], v[136:139], v[144:147], v[112:127]
	v_mfma_f32_32x32x16_bf16 v[112:127], v[140:143], v[148:151], v[112:127]
	ds_read_b64_tr_b16 v[144:145], v152 offset:0x200
	ds_read_b64_tr_b16 v[146:147], v152 offset:0xa00
	ds_read_b64_tr_b16 v[148:149], v152 offset:0x1200
	ds_read_b64_tr_b16 v[150:151], v152 offset:0x1a00
	s_waitcnt lgkmcnt(4)
	v_mfma_f32_32x32x16_bf16 v[112:127], v[128:131], v[228:231], v[112:127]
	v_mfma_f32_32x32x16_bf16 v[112:127], v[132:135], v[232:235], v[112:127]
	ds_read_b64_tr_b16 v[228:229], v152 offset:0x2200
	ds_read_b64_tr_b16 v[230:231], v152 offset:0x2a00
	ds_read_b64_tr_b16 v[232:233], v152 offset:0x3200
	ds_read_b64_tr_b16 v[234:235], v152 offset:0x3a00
	s_waitcnt lgkmcnt(4)
	v_mfma_f32_32x32x16_bf16 v[96:111], v[136:139], v[144:147], v[96:111]
	v_mfma_f32_32x32x16_bf16 v[96:111], v[140:143], v[148:151], v[96:111]
	ds_read_b64_tr_b16 v[144:145], v152 offset:0x400
	ds_read_b64_tr_b16 v[146:147], v152 offset:0xc00
	ds_read_b64_tr_b16 v[148:149], v152 offset:0x1400
	ds_read_b64_tr_b16 v[150:151], v152 offset:0x1c00
	s_waitcnt lgkmcnt(4)
	v_mfma_f32_32x32x16_bf16 v[96:111], v[128:131], v[228:231], v[96:111]
	v_mfma_f32_32x32x16_bf16 v[96:111], v[132:135], v[232:235], v[96:111]
	ds_read_b64_tr_b16 v[228:229], v152 offset:0x2400
	ds_read_b64_tr_b16 v[230:231], v152 offset:0x2c00
	ds_read_b64_tr_b16 v[232:233], v152 offset:0x3400
	ds_read_b64_tr_b16 v[234:235], v152 offset:0x3c00
	s_waitcnt lgkmcnt(4)
; #define SBAR() __builtin_amdgcn_sched_barrier(0)
; template <int OFF> __device__ __forceinline__ s16x4 tr_read(int vb) { s16x4 r; asm volatile("ds_read_b64_tr_b16 %0, %1 offset:%2" : "=&v"(r) : "v"(vb), "i"(OFF) : "memory"); return r; }
; #define WAIT_BAR_0() asm volatile("s_waitcnt vmcnt(0) lgkmcnt(0)\n\ts_barrier" ::: "memory")
; #define WAIT_BAR_0() asm volatile("s_waitcnt vmcnt(0) lgkmcnt(0)\n\ts_barrier" ::: "memory")
; #define WAIT_BAR_0() asm volatile("s_waitcnt vmcnt(0) lgkmcnt(0)\n\ts_barrier" ::: "memory")
; template <int D0> __device__ __forceinline__ void pv_one_lean(f32x16& od, int vb, bf16x8 pa0, bf16x8 pa1, bf16x8 pa2, bf16x8 pa3) {
;     ...
;   { const s16x4 l0 = tr_read<v_rd_off(D0, 0, 0)>(vb), h0 = tr_read<v_rd_off(D0, 0, 1)>(vb), l1 = tr_read<v_rd_off(D0, 1, 0)>(vb), h1 = tr_read<v_rd_off(D0, 1, 1)>(vb);
;     asm volatile("s_waitcnt lgkmcnt(0)" ::: "memory"); SBAR();
;     od = __builtin_amdgcn_mfma_f32_32x32x16_bf16(pa0, PKL(l0, h0), od, 0, 0, 0); od = __builtin_amdgcn_mfma_f32_32x32x16_bf16(pa1, PKL(l1, h1), od, 0, 0, 0); }
;   SBAR();
;   { const s16x4 l2 = tr_read<v_rd_off(D0, 2, 0)>(vb), h2 = tr_read<v_rd_off(D0, 2, 1)>(vb), l3 = tr_read<v_rd_off(D0, 3, 0)>(vb), h3 = tr_read<v_rd_off(D0, 3, 1)>(vb);
;     asm volatile("s_waitcnt lgkmcnt(0)" ::: "memory"); SBAR();
;     od = __builtin_amdgcn_mfma_f32_32x32x16_bf16(pa2, PKL(l2, h2), od, 0, 0, 0); od = __builtin_amdgcn_mfma_f32_32x32x16_bf16(pa3, PKL(l3, h3), od, 0, 0, 0); }
;     ...
; }
; __device__ __forceinline__ void pv_d0_lean(f32x16* o, int vb, bf16x8 pa0, bf16x8 pa1, bf16x8 pa2, bf16x8 pa3) {
;   pv_one_lean<0>(o[0], vb, pa0, pa1, pa2, pa3); SBAR(); pv_one_lean<1>(o[1], vb, pa0, pa1, pa2, pa3); SBAR(); pv_one_lean<2>(o[2], vb, pa0, pa1, pa2, pa3); SBAR(); pv_one_lean<3>(o[3], vb, pa0, pa1, pa2, pa3);
; }
; template <int MODE>
; __device__ __forceinline__ void attn_unit_ml(const AttnUnit& U, char* lds) {
;     ...
;     pv_d0_lean(o, vb0 + st * SHM_V2, pa0, pa1, pa2, pa3); SBAR();
;     pv_d0_lean(o + 4, vb0 + st * SHM_V2 + 16384, pa0, pa1, pa2, pa3);
;     WAIT_BAR_0();
	v_mfma_f32_32x32x16_bf16 v[80:95], v[136:139], v[144:147], v[80:95]
	v_mfma_f32_32x32x16_bf16 v[80:95], v[140:143], v[148:151], v[80:95]
	ds_read_b64_tr_b16 v[144:145], v152 offset:0x600
	ds_read_b64_tr_b16 v[146:147], v152 offset:0xe00
	ds_read_b64_tr_b16 v[148:149], v152 offset:0x1600
	ds_read_b64_tr_b16 v[150:151], v152 offset:0x1e00
	s_waitcnt lgkmcnt(4)
	v_mfma_f32_32x32x16_bf16 v[80:95], v[128:131], v[228:231], v[80:95]
	v_mfma_f32_32x32x16_bf16 v[80:95], v[132:135], v[232:235], v[80:95]
	ds_read_b64_tr_b16 v[228:229], v152 offset:0x2600
	ds_read_b64_tr_b16 v[230:231], v152 offset:0x2e00
	ds_read_b64_tr_b16 v[232:233], v152 offset:0x3600
	ds_read_b64_tr_b16 v[234:235], v152 offset:0x3e00
	s_waitcnt lgkmcnt(4)
	v_mfma_f32_32x32x16_bf16 v[64:79], v[136:139], v[144:147], v[64:79]
	v_mfma_f32_32x32x16_bf16 v[64:79], v[140:143], v[148:151], v[64:79]
	v_add_u32_e32 v152, 0x4000, v152
	ds_read_b64_tr_b16 v[144:145], v152 offset:0
	ds_read_b64_tr_b16 v[146:147], v152 offset:0x800
	ds_read_b64_tr_b16 v[148:149], v152 offset:0x1000
	ds_read_b64_tr_b16 v[150:151], v152 offset:0x1800
	s_waitcnt lgkmcnt(4)
	v_mfma_f32_32x32x16_bf16 v[64:79], v[128:131], v[228:231], v[64:79]
	v_mfma_f32_32x32x16_bf16 v[64:79], v[132:135], v[232:235], v[64:79]
	ds_read_b64_tr_b16 v[228:229], v152 offset:0x2000
	ds_read_b64_tr_b16 v[230:231], v152 offset:0x2800
	ds_read_b64_tr_b16 v[232:233], v152 offset:0x3000
	ds_read_b64_tr_b16 v[234:235], v152 offset:0x3800
	s_waitcnt lgkmcnt(4)
	v_mfma_f32_32x32x16_bf16 v[48:63], v[136:139], v[144:147], v[48:63]
	v_mfma_f32_32x32x16_bf16 v[48:63], v[140:143], v[148:151], v[48:63]
	ds_read_b64_tr_b16 v[144:145], v152 offset:0x200
	ds_read_b64_tr_b16 v[146:147], v152 offset:0xa00
	ds_read_b64_tr_b16 v[148:149], v152 offset:0x1200
	ds_read_b64_tr_b16 v[150:151], v152 offset:0x1a00
	s_waitcnt lgkmcnt(4)
	v_mfma_f32_32x32x16_bf16 v[48:63], v[128:131], v[228:231], v[48:63]
	v_mfma_f32_32x32x16_bf16 v[48:63], v[132:135], v[232:235], v[48:63]
	ds_read_b64_tr_b16 v[228:229], v152 offset:0x2200
	ds_read_b64_tr_b16 v[230:231], v152 offset:0x2a00
	ds_read_b64_tr_b16 v[232:233], v152 offset:0x3200
	ds_read_b64_tr_b16 v[234:235], v152 offset:0x3a00
	s_waitcnt lgkmcnt(4)
	v_mfma_f32_32x32x16_bf16 v[32:47], v[136:139], v[144:147], v[32:47]
	v_mfma_f32_32x32x16_bf16 v[32:47], v[140:143], v[148:151], v[32:47]
	ds_read_b64_tr_b16 v[144:145], v152 offset:0x400
	ds_read_b64_tr_b16 v[146:147], v152 offset:0xc00
	ds_read_b64_tr_b16 v[148:149], v152 offset:0x1400
	ds_read_b64_tr_b16 v[150:151], v152 offset:0x1c00
	s_waitcnt lgkmcnt(4)
	v_mfma_f32_32x32x16_bf16 v[32:47], v[128:131], v[228:231], v[32:47]
	v_mfma_f32_32x32x16_bf16 v[32:47], v[132:135], v[232:235], v[32:47]
	ds_read_b64_tr_b16 v[228:229], v152 offset:0x2400
	ds_read_b64_tr_b16 v[230:231], v152 offset:0x2c00
	ds_read_b64_tr_b16 v[232:233], v152 offset:0x3400
	ds_read_b64_tr_b16 v[234:235], v152 offset:0x3c00
	s_waitcnt lgkmcnt(4)
	v_mfma_f32_32x32x16_bf16 v[16:31], v[136:139], v[144:147], v[16:31]
	v_mfma_f32_32x32x16_bf16 v[16:31], v[140:143], v[148:151], v[16:31]
	ds_read_b64_tr_b16 v[144:145], v152 offset:0x600
	ds_read_b64_tr_b16 v[146:147], v152 offset:0xe00
	ds_read_b64_tr_b16 v[148:149], v152 offset:0x1600
	ds_read_b64_tr_b16 v[150:151], v152 offset:0x1e00
	s_waitcnt lgkmcnt(4)
	v_mfma_f32_32x32x16_bf16 v[16:31], v[128:131], v[228:231], v[16:31]
	v_mfma_f32_32x32x16_bf16 v[16:31], v[132:135], v[232:235], v[16:31]
	ds_read_b64_tr_b16 v[228:229], v152 offset:0x2600
	ds_read_b64_tr_b16 v[230:231], v152 offset:0x2e00
	ds_read_b64_tr_b16 v[232:233], v152 offset:0x3600
	ds_read_b64_tr_b16 v[234:235], v152 offset:0x3e00
	s_waitcnt lgkmcnt(4)
	v_mfma_f32_32x32x16_bf16 v[0:15], v[136:139], v[144:147], v[0:15]
	v_mfma_f32_32x32x16_bf16 v[0:15], v[140:143], v[148:151], v[0:15]
	s_waitcnt lgkmcnt(0)
	v_mfma_f32_32x32x16_bf16 v[0:15], v[128:131], v[228:231], v[0:15]
	v_mfma_f32_32x32x16_bf16 v[0:15], v[132:135], v[232:235], v[0:15]
	s_add_i32 s86, s86, 64
	s_add_u32 s58, s58, 0x80000
	s_addc_u32 s59, s59, 0
	s_add_u32 s60, s60, 0x80000
	s_waitcnt vmcnt(0) lgkmcnt(0)
	s_barrier
	s_addc_u32 s61, s61, 0
	s_add_i32 s84, s84, 1
	s_add_i32 s11, s41, s84
	v_add_u32_e32 v222, 0x100, v222
	v_subrev_u32_e32 v223, 64, v223
	s_cmp_eq_u32 s11, 1
	s_cbranch_scc1 .LBB0_1047

; template <int MODE> __device__ __forceinline__ void partialW2(f32x16& p0, f32x16& p1, const float* auxk, bool band, int qrel, int hi) {
; #pragma unroll
;   for (int g = 0; g < 4; ++g) { const f32x4 a = *(const f32x4*)(auxk + 8 * g + 4 * hi), b = *(const f32x4*)(auxk + 32 + 8 * g + 4 * hi);
; #pragma unroll
;     for (int e = 0; e < 4; ++e) { p0[4 * g + e] *= a[e]; p1[4 * g + e] *= b[e]; } }
;   if (band) {
; #pragma unroll
;     for (int r = 0; r < 16; ++r) { const int kvl = (r & 3) + 8 * (r >> 2);
;       const bool k0 = (MODE == 2) ? (kvl <= qrel) : (kvl >= qrel), k1 = (MODE == 2) ? (kvl + 32 <= qrel) : (kvl + 32 >= qrel);
;       p0[r] = k0 ? p0[r] : 0.f; p1[r] = k1 ? p1[r] : 0.f; }
;   }
; }
; template <int DQK> __device__ __forceinline__ void qkt_acc(f32x16& p0, f32x16& p1, const char* Ks, const bf16x8* qr, int r32, int hi) {
;   constexpr int ROWB = DQK * 2;
;   const int sw = (r32 & 7) << 4; const char* k0p = Ks + r32 * ROWB; const char* k1p = Ks + (32 + r32) * ROWB;
; #pragma unroll
;   for (int d0 = 0; d0 < DQK / 16; ++d0) { const int cb = ((d0 * 16 + hi * 8) * 2) ^ sw;
;     const bf16x8 b0 = *reinterpret_cast<const bf16x8*>(k0p + cb);
;     const bf16x8 b1 = *reinterpret_cast<const bf16x8*>(k1p + cb);
;     p0 = __builtin_amdgcn_mfma_f32_32x32x16_bf16(b0, qr[d0], p0, 0, 0, 0);
;     p1 = __builtin_amdgcn_mfma_f32_32x32x16_bf16(b1, qr[d0], p1, 0, 0, 0); }
; }
.LBB0_1045:
	v_add_u32_e32 v192, s90, v211
	v_add_u32_e32 v200, v192, v212
	ds_read_b128 v[196:199], v200
	ds_read_b128 v[228:231], v200 offset:8192
	v_add_u32_e32 v200, v192, v213
	ds_read_b128 v[232:235], v200
	ds_read_b128 v[244:247], v200 offset:8192
	s_waitcnt lgkmcnt(2)
	v_mfma_f32_32x32x16_bf16 v[128:143], v[196:199], v[160:163], 0
	v_mfma_f32_32x32x16_bf16 v[144:159], v[228:231], v[160:163], 0
	v_add_u32_e32 v200, v192, v215
	ds_read_b128 v[196:199], v200
	ds_read_b128 v[228:231], v200 offset:8192
	s_waitcnt lgkmcnt(2)
	v_mfma_f32_32x32x16_bf16 v[128:143], v[232:235], v[164:167], v[128:143]
	v_mfma_f32_32x32x16_bf16 v[144:159], v[244:247], v[164:167], v[144:159]
	v_add_u32_e32 v200, v192, v216
	ds_read_b128 v[232:235], v200
	ds_read_b128 v[244:247], v200 offset:8192
	s_waitcnt lgkmcnt(2)
	v_mfma_f32_32x32x16_bf16 v[128:143], v[196:199], v[168:171], v[128:143]
	v_mfma_f32_32x32x16_bf16 v[144:159], v[228:231], v[168:171], v[144:159]
	v_add_u32_e32 v200, v192, v217
	ds_read_b128 v[196:199], v200
	ds_read_b128 v[228:231], v200 offset:8192
	s_waitcnt lgkmcnt(2)
	v_mfma_f32_32x32x16_bf16 v[128:143], v[232:235], v[172:175], v[128:143]
	v_mfma_f32_32x32x16_bf16 v[144:159], v[244:247], v[172:175], v[144:159]
	v_add_u32_e32 v200, v192, v218
	ds_read_b128 v[232:235], v200
	ds_read_b128 v[244:247], v200 offset:8192
	s_waitcnt lgkmcnt(2)
	v_mfma_f32_32x32x16_bf16 v[128:143], v[196:199], v[176:179], v[128:143]
	v_mfma_f32_32x32x16_bf16 v[144:159], v[228:231], v[176:179], v[144:159]
	v_add_u32_e32 v200, v192, v219
	ds_read_b128 v[196:199], v200
	ds_read_b128 v[228:231], v200 offset:8192
	s_waitcnt lgkmcnt(2)
	v_mfma_f32_32x32x16_bf16 v[128:143], v[232:235], v[180:183], v[128:143]
	v_mfma_f32_32x32x16_bf16 v[144:159], v[244:247], v[180:183], v[144:159]
	v_add_u32_e32 v200, v192, v220
	ds_read_b128 v[232:235], v200
	ds_read_b128 v[244:247], v200 offset:8192
	s_waitcnt lgkmcnt(2)
	v_mfma_f32_32x32x16_bf16 v[128:143], v[196:199], v[184:187], v[128:143]
	v_mfma_f32_32x32x16_bf16 v[144:159], v[228:231], v[184:187], v[144:159]
	s_waitcnt lgkmcnt(0)
	v_mfma_f32_32x32x16_bf16 v[128:143], v[232:235], v[188:191], v[128:143]
	v_mfma_f32_32x32x16_bf16 v[144:159], v[244:247], v[188:191], v[144:159]
	s_nop 1
	ds_read_b128 v[196:199], v222
	ds_read_b128 v[200:203], v222 offset:32
	ds_read_b128 v[224:227], v222 offset:128
	s_cmp_ge_u32 s86, s85
	s_waitcnt lgkmcnt(2)
	s_nop 3
	v_pk_mul_f32 v[196:197], v[128:129], v[196:197]
	s_waitcnt lgkmcnt(0)
	s_nop 0
	v_pk_mul_f32 v[128:129], v[144:145], v[224:225]
	v_pk_mul_f32 v[144:145], v[130:131], v[198:199]
	v_pk_mul_f32 v[130:131], v[146:147], v[226:227]
	ds_read_b128 v[224:227], v222 offset:160
	v_pk_mul_f32 v[198:199], v[132:133], v[200:201]
	v_pk_mul_f32 v[200:201], v[134:135], v[202:203]
	s_waitcnt lgkmcnt(0)
	v_pk_mul_f32 v[132:133], v[148:149], v[224:225]
	ds_read_b128 v[146:149], v222 offset:64
	ds_read_b128 v[202:205], v222 offset:192
	v_pk_mul_f32 v[134:135], v[150:151], v[226:227]
	s_waitcnt lgkmcnt(1)
	v_pk_mul_f32 v[150:151], v[136:137], v[146:147]
	s_waitcnt lgkmcnt(0)
	v_pk_mul_f32 v[146:147], v[152:153], v[202:203]
	v_pk_mul_f32 v[152:153], v[138:139], v[148:149]
	ds_read_b128 v[136:139], v222 offset:96
	ds_read_b128 v[224:227], v222 offset:224
	v_pk_mul_f32 v[148:149], v[154:155], v[204:205]
	s_waitcnt lgkmcnt(1)
	v_pk_mul_f32 v[202:203], v[140:141], v[136:137]
	s_waitcnt lgkmcnt(0)
	v_pk_mul_f32 v[154:155], v[156:157], v[224:225]
	v_pk_mul_f32 v[204:205], v[142:143], v[138:139]
	v_pk_mul_f32 v[156:157], v[158:159], v[226:227]
	s_cbranch_scc1 .LBB0_1040
	v_cmp_gt_i32_e32 vcc, 1, v223
	s_nop 1
	v_cndmask_b32_e32 v196, 0, v196, vcc
	v_cmp_gt_i32_e32 vcc, 2, v223
	s_nop 1
	v_cndmask_b32_e32 v197, 0, v197, vcc
	v_cmp_gt_i32_e32 vcc, 3, v223
	s_nop 1
	v_cndmask_b32_e32 v144, 0, v144, vcc
	v_cmp_gt_i32_e32 vcc, 4, v223
	s_nop 1
	v_cndmask_b32_e32 v145, 0, v145, vcc
	v_cmp_gt_i32_e32 vcc, 9, v223
	s_nop 1
	v_cndmask_b32_e32 v198, 0, v198, vcc
	v_cmp_gt_i32_e32 vcc, 10, v223
	s_nop 1
	v_cndmask_b32_e32 v199, 0, v199, vcc
	v_cmp_gt_i32_e32 vcc, 11, v223
	s_nop 1
	v_cndmask_b32_e32 v200, 0, v200, vcc
	v_cmp_gt_i32_e32 vcc, 12, v223
	s_nop 1
	v_cndmask_b32_e32 v201, 0, v201, vcc
	v_cmp_gt_i32_e32 vcc, 17, v223
	s_nop 1
	v_cndmask_b32_e32 v150, 0, v150, vcc
	v_cmp_gt_i32_e32 vcc, 18, v223
	s_nop 1
	v_cndmask_b32_e32 v151, 0, v151, vcc
	v_cmp_gt_i32_e32 vcc, 19, v223
	s_nop 1
	v_cndmask_b32_e32 v152, 0, v152, vcc
	v_cmp_gt_i32_e32 vcc, 20, v223
	s_nop 1
	v_cndmask_b32_e32 v153, 0, v153, vcc
	v_cmp_gt_i32_e32 vcc, 25, v223
	s_nop 1
	v_cndmask_b32_e32 v202, 0, v202, vcc
	v_cmp_gt_i32_e32 vcc, 26, v223
	s_nop 1
	v_cndmask_b32_e32 v203, 0, v203, vcc
	v_cmp_gt_i32_e32 vcc, 27, v223
	s_nop 1
	v_cndmask_b32_e32 v204, 0, v204, vcc
	v_cmp_gt_i32_e32 vcc, 28, v223
	s_nop 1
	v_cndmask_b32_e32 v205, 0, v205, vcc
	v_cmp_gt_i32_e32 vcc, 33, v223
	s_nop 1
	v_cndmask_b32_e32 v128, 0, v128, vcc
	v_cmp_gt_i32_e32 vcc, 34, v223
	s_nop 1
	v_cndmask_b32_e32 v129, 0, v129, vcc
	v_cmp_gt_i32_e32 vcc, 35, v223
	s_nop 1
	v_cndmask_b32_e32 v130, 0, v130, vcc
	v_cmp_gt_i32_e32 vcc, 36, v223
	s_nop 1
	v_cndmask_b32_e32 v131, 0, v131, vcc
	v_cmp_gt_i32_e32 vcc, 41, v223
	s_nop 1
	v_cndmask_b32_e32 v132, 0, v132, vcc
	v_cmp_gt_i32_e32 vcc, 42, v223
	s_nop 1
	v_cndmask_b32_e32 v133, 0, v133, vcc
	v_cmp_gt_i32_e32 vcc, 43, v223
	s_nop 1
	v_cndmask_b32_e32 v134, 0, v134, vcc
	v_cmp_gt_i32_e32 vcc, 44, v223
	s_nop 1
	v_cndmask_b32_e32 v135, 0, v135, vcc
	v_cmp_gt_i32_e32 vcc, 49, v223
	s_nop 1
	v_cndmask_b32_e32 v146, 0, v146, vcc
	v_cmp_gt_i32_e32 vcc, 50, v223
	s_nop 1
	v_cndmask_b32_e32 v147, 0, v147, vcc
	v_cmp_gt_i32_e32 vcc, 51, v223
	s_nop 1
	v_cndmask_b32_e32 v148, 0, v148, vcc
	v_cmp_gt_i32_e32 vcc, 52, v223
	s_nop 1
	v_cndmask_b32_e32 v149, 0, v149, vcc
	v_cmp_gt_i32_e32 vcc, 57, v223
	s_nop 1
	v_cndmask_b32_e32 v154, 0, v154, vcc
	v_cmp_gt_i32_e32 vcc, 58, v223
	s_nop 1
	v_cndmask_b32_e32 v155, 0, v155, vcc
	v_cmp_gt_i32_e32 vcc, 59, v223
	s_nop 1
	v_cndmask_b32_e32 v156, 0, v156, vcc
	v_cmp_gt_i32_e32 vcc, 60, v223
	s_nop 1
	v_cndmask_b32_e32 v157, 0, v157, vcc
	s_branch .LBB0_1040

; #define SBAR() __builtin_amdgcn_sched_barrier(0)
; template <int OFF> __device__ __forceinline__ s16x4 tr_read(int vb) { s16x4 r; asm volatile("ds_read_b64_tr_b16 %0, %1 offset:%2" : "=&v"(r) : "v"(vb), "i"(OFF) : "memory"); return r; }
; __device__ __forceinline__ void finishW(f32x16& p0, f32x16& p1, float& l_reg, bf16x8& pa0, bf16x8& pa1, bf16x8& pa2, bf16x8& pa3) {
;   float ps = 0;
; #pragma unroll
;   for (int r = 0; r < 16; ++r) ps += p0[r];
; #pragma unroll
;   for (int r = 0; r < 16; ++r) ps += p1[r];
;   { auto rr = __builtin_amdgcn_permlane32_swap(__float_as_uint(ps), __float_as_uint(ps), false, false);
;     ps = __uint_as_float(rr[0]) + __uint_as_float(rr[1]); }
;   l_reg += ps;
;   PK4(p0, 0, pa0); PK4(p0, 8, pa1); PK4(p1, 0, pa2); PK4(p1, 8, pa3);
; }
; template <int D0> __device__ __forceinline__ void pv_one_lean(f32x16& od, int vb, bf16x8 pa0, bf16x8 pa1, bf16x8 pa2, bf16x8 pa3) {
;     ...
;   { const s16x4 l0 = tr_read<v_rd_off(D0, 0, 0)>(vb), h0 = tr_read<v_rd_off(D0, 0, 1)>(vb), l1 = tr_read<v_rd_off(D0, 1, 0)>(vb), h1 = tr_read<v_rd_off(D0, 1, 1)>(vb);
;     asm volatile("s_waitcnt lgkmcnt(0)" ::: "memory"); SBAR();
;     od = __builtin_amdgcn_mfma_f32_32x32x16_bf16(pa0, PKL(l0, h0), od, 0, 0, 0); od = __builtin_amdgcn_mfma_f32_32x32x16_bf16(pa1, PKL(l1, h1), od, 0, 0, 0); }
;   SBAR();
;   { const s16x4 l2 = tr_read<v_rd_off(D0, 2, 0)>(vb), h2 = tr_read<v_rd_off(D0, 2, 1)>(vb), l3 = tr_read<v_rd_off(D0, 3, 0)>(vb), h3 = tr_read<v_rd_off(D0, 3, 1)>(vb);
;     asm volatile("s_waitcnt lgkmcnt(0)" ::: "memory"); SBAR();
;     od = __builtin_amdgcn_mfma_f32_32x32x16_bf16(pa2, PKL(l2, h2), od, 0, 0, 0); od = __builtin_amdgcn_mfma_f32_32x32x16_bf16(pa3, PKL(l3, h3), od, 0, 0, 0); }
;     ...
; }
; __device__ __forceinline__ void pv_d0_lean(f32x16* o, int vb, bf16x8 pa0, bf16x8 pa1, bf16x8 pa2, bf16x8 pa3) {
;   pv_one_lean<0>(o[0], vb, pa0, pa1, pa2, pa3); SBAR(); pv_one_lean<1>(o[1], vb, pa0, pa1, pa2, pa3); SBAR(); pv_one_lean<2>(o[2], vb, pa0, pa1, pa2, pa3); SBAR(); pv_one_lean<3>(o[3], vb, pa0, pa1, pa2, pa3);
; }
.LBB0_1055:
	v_add_f32_e32 v132, 0, v196
	v_add_f32_e32 v132, v197, v132
	v_add_f32_e32 v132, v144, v132
	v_add_f32_e32 v132, v145, v132
	v_add_f32_e32 v132, v198, v132
	v_add_f32_e32 v132, v199, v132
	v_add_f32_e32 v132, v200, v132
	v_add_f32_e32 v132, v201, v132
	v_add_f32_e32 v132, v136, v132
	v_add_f32_e32 v132, v137, v132
	v_add_f32_e32 v132, v138, v132
	v_add_f32_e32 v132, v139, v132
	v_add_f32_e32 v132, v140, v132
	v_add_f32_e32 v132, v141, v132
	v_add_f32_e32 v132, v142, v132
	v_add_f32_e32 v132, v143, v132
	v_add_f32_e32 v132, v128, v132
	v_add_f32_e32 v132, v129, v132
	v_add_f32_e32 v132, v130, v132
	v_add_f32_e32 v132, v131, v132
	v_add_f32_e32 v132, v146, v132
	v_add_f32_e32 v132, v147, v132
	v_add_f32_e32 v132, v148, v132
	v_add_f32_e32 v132, v149, v132
	v_add_f32_e32 v132, v150, v132
	v_add_f32_e32 v132, v151, v132
	v_add_f32_e32 v132, v152, v132
	v_add_f32_e32 v132, v153, v132
	v_add_f32_e32 v132, v154, v132
	v_add_f32_e32 v132, v155, v132
	v_add_f32_e32 v132, v156, v132
	v_add_f32_e32 v132, v157, v132
	v_mov_b32_e32 v133, v132
	s_nop 1
	v_permlane32_swap_b32_e32 v132, v133
	v_add_f32_e32 v132, v132, v133
	v_add_f32_e32 v209, v209, v132
	v_cvt_pk_bf16_f32 v132, v196, v197
	v_cvt_pk_bf16_f32 v133, v144, v145
	v_cvt_pk_bf16_f32 v134, v198, v199
	v_cvt_pk_bf16_f32 v135, v200, v201
	v_cvt_pk_bf16_f32 v136, v136, v137
	v_cvt_pk_bf16_f32 v137, v138, v139
	v_cvt_pk_bf16_f32 v138, v140, v141
	v_cvt_pk_bf16_f32 v139, v142, v143
	v_cvt_pk_bf16_f32 v140, v128, v129
	v_cvt_pk_bf16_f32 v141, v130, v131
	v_cvt_pk_bf16_f32 v142, v146, v147
	v_cvt_pk_bf16_f32 v143, v148, v149
	v_cvt_pk_bf16_f32 v128, v150, v151
	v_cvt_pk_bf16_f32 v129, v152, v153
	v_cvt_pk_bf16_f32 v130, v154, v155
	v_cvt_pk_bf16_f32 v131, v156, v157
	v_permlane32_swap_b32_e32 v132, v134
	v_permlane32_swap_b32_e32 v133, v135
	v_permlane32_swap_b32_e32 v136, v138
	v_permlane32_swap_b32_e32 v137, v139
	v_permlane32_swap_b32_e32 v140, v142
	v_permlane32_swap_b32_e32 v141, v143
	v_permlane32_swap_b32_e32 v128, v130
	v_permlane32_swap_b32_e32 v129, v131
	v_lshl_add_u32 v152, s59, 15, v217
	ds_read_b64_tr_b16 v[144:145], v152 offset:0
	ds_read_b64_tr_b16 v[146:147], v152 offset:0x800
	ds_read_b64_tr_b16 v[148:149], v152 offset:0x1000
	ds_read_b64_tr_b16 v[150:151], v152 offset:0x1800
	ds_read_b64_tr_b16 v[228:229], v152 offset:0x2000
	ds_read_b64_tr_b16 v[230:231], v152 offset:0x2800
	ds_read_b64_tr_b16 v[232:233], v152 offset:0x3000
	ds_read_b64_tr_b16 v[234:235], v152 offset:0x3800
	s_waitcnt lgkmcnt(4)
	v_mfma_f32_32x32x16_bf16 v[112:127], v[132:135], v[144:147], v[112:127]
	v_mfma_f32_32x32x16_bf16 v[112:127], v[136:139], v[148:151], v[112:127]
	ds_read_b64_tr_b16 v[144:145], v152 offset:0x200
	ds_read_b64_tr_b16 v[146:147], v152 offset:0xa00
	ds_read_b64_tr_b16 v[148:149], v152 offset:0x1200
	ds_read_b64_tr_b16 v[150:151], v152 offset:0x1a00
	s_waitcnt lgkmcnt(4)
	v_mfma_f32_32x32x16_bf16 v[112:127], v[140:143], v[228:231], v[112:127]
	v_mfma_f32_32x32x16_bf16 v[112:127], v[128:131], v[232:235], v[112:127]
	ds_read_b64_tr_b16 v[228:229], v152 offset:0x2200
	ds_read_b64_tr_b16 v[230:231], v152 offset:0x2a00
	ds_read_b64_tr_b16 v[232:233], v152 offset:0x3200
	ds_read_b64_tr_b16 v[234:235], v152 offset:0x3a00
	s_waitcnt lgkmcnt(4)
	v_mfma_f32_32x32x16_bf16 v[96:111], v[132:135], v[144:147], v[96:111]
	v_mfma_f32_32x32x16_bf16 v[96:111], v[136:139], v[148:151], v[96:111]
	ds_read_b64_tr_b16 v[144:145], v152 offset:0x400
	ds_read_b64_tr_b16 v[146:147], v152 offset:0xc00
	ds_read_b64_tr_b16 v[148:149], v152 offset:0x1400
	ds_read_b64_tr_b16 v[150:151], v152 offset:0x1c00
	s_waitcnt lgkmcnt(4)
	v_mfma_f32_32x32x16_bf16 v[96:111], v[140:143], v[228:231], v[96:111]
	v_mfma_f32_32x32x16_bf16 v[96:111], v[128:131], v[232:235], v[96:111]
	ds_read_b64_tr_b16 v[228:229], v152 offset:0x2400
	ds_read_b64_tr_b16 v[230:231], v152 offset:0x2c00
	ds_read_b64_tr_b16 v[232:233], v152 offset:0x3400
	ds_read_b64_tr_b16 v[234:235], v152 offset:0x3c00
	s_waitcnt lgkmcnt(4)
; #define SBAR() __builtin_amdgcn_sched_barrier(0)
; template <int OFF> __device__ __forceinline__ s16x4 tr_read(int vb) { s16x4 r; asm volatile("ds_read_b64_tr_b16 %0, %1 offset:%2" : "=&v"(r) : "v"(vb), "i"(OFF) : "memory"); return r; }
; #define WAIT_BAR_0() asm volatile("s_waitcnt vmcnt(0) lgkmcnt(0)\n\ts_barrier" ::: "memory")
; #define WAIT_BAR_0() asm volatile("s_waitcnt vmcnt(0) lgkmcnt(0)\n\ts_barrier" ::: "memory")
; #define WAIT_BAR_0() asm volatile("s_waitcnt vmcnt(0) lgkmcnt(0)\n\ts_barrier" ::: "memory")
; template <int D0> __device__ __forceinline__ void pv_one_lean(f32x16& od, int vb, bf16x8 pa0, bf16x8 pa1, bf16x8 pa2, bf16x8 pa3) {
;     ...
;   { const s16x4 l0 = tr_read<v_rd_off(D0, 0, 0)>(vb), h0 = tr_read<v_rd_off(D0, 0, 1)>(vb), l1 = tr_read<v_rd_off(D0, 1, 0)>(vb), h1 = tr_read<v_rd_off(D0, 1, 1)>(vb);
;     asm volatile("s_waitcnt lgkmcnt(0)" ::: "memory"); SBAR();
;     od = __builtin_amdgcn_mfma_f32_32x32x16_bf16(pa0, PKL(l0, h0), od, 0, 0, 0); od = __builtin_amdgcn_mfma_f32_32x32x16_bf16(pa1, PKL(l1, h1), od, 0, 0, 0); }
;   SBAR();
;   { const s16x4 l2 = tr_read<v_rd_off(D0, 2, 0)>(vb), h2 = tr_read<v_rd_off(D0, 2, 1)>(vb), l3 = tr_read<v_rd_off(D0, 3, 0)>(vb), h3 = tr_read<v_rd_off(D0, 3, 1)>(vb);
;     asm volatile("s_waitcnt lgkmcnt(0)" ::: "memory"); SBAR();
;     od = __builtin_amdgcn_mfma_f32_32x32x16_bf16(pa2, PKL(l2, h2), od, 0, 0, 0); od = __builtin_amdgcn_mfma_f32_32x32x16_bf16(pa3, PKL(l3, h3), od, 0, 0, 0); }
;     ...
; }
; __device__ __forceinline__ void pv_d0_lean(f32x16* o, int vb, bf16x8 pa0, bf16x8 pa1, bf16x8 pa2, bf16x8 pa3) {
;   pv_one_lean<0>(o[0], vb, pa0, pa1, pa2, pa3); SBAR(); pv_one_lean<1>(o[1], vb, pa0, pa1, pa2, pa3); SBAR(); pv_one_lean<2>(o[2], vb, pa0, pa1, pa2, pa3); SBAR(); pv_one_lean<3>(o[3], vb, pa0, pa1, pa2, pa3);
; }
; template <int MODE>
; __device__ __forceinline__ void attn_unit_ml(const AttnUnit& U, char* lds) {
;     ...
;     pv_d0_lean(o, vb0 + st * SHM_V2, pa0, pa1, pa2, pa3); SBAR();
;     pv_d0_lean(o + 4, vb0 + st * SHM_V2 + 16384, pa0, pa1, pa2, pa3);
;     WAIT_BAR_0();
	v_mfma_f32_32x32x16_bf16 v[80:95], v[132:135], v[144:147], v[80:95]
	v_mfma_f32_32x32x16_bf16 v[80:95], v[136:139], v[148:151], v[80:95]
	ds_read_b64_tr_b16 v[144:145], v152 offset:0x600
	ds_read_b64_tr_b16 v[146:147], v152 offset:0xe00
	ds_read_b64_tr_b16 v[148:149], v152 offset:0x1600
	ds_read_b64_tr_b16 v[150:151], v152 offset:0x1e00
	s_waitcnt lgkmcnt(4)
	v_mfma_f32_32x32x16_bf16 v[80:95], v[140:143], v[228:231], v[80:95]
	v_mfma_f32_32x32x16_bf16 v[80:95], v[128:131], v[232:235], v[80:95]
	ds_read_b64_tr_b16 v[228:229], v152 offset:0x2600
	ds_read_b64_tr_b16 v[230:231], v152 offset:0x2e00
	ds_read_b64_tr_b16 v[232:233], v152 offset:0x3600
	ds_read_b64_tr_b16 v[234:235], v152 offset:0x3e00
	s_waitcnt lgkmcnt(4)
	v_mfma_f32_32x32x16_bf16 v[64:79], v[132:135], v[144:147], v[64:79]
	v_mfma_f32_32x32x16_bf16 v[64:79], v[136:139], v[148:151], v[64:79]
	v_add_u32_e32 v152, 0x4000, v152
	ds_read_b64_tr_b16 v[144:145], v152 offset:0
	ds_read_b64_tr_b16 v[146:147], v152 offset:0x800
	ds_read_b64_tr_b16 v[148:149], v152 offset:0x1000
	ds_read_b64_tr_b16 v[150:151], v152 offset:0x1800
	s_waitcnt lgkmcnt(4)
	v_mfma_f32_32x32x16_bf16 v[64:79], v[140:143], v[228:231], v[64:79]
	v_mfma_f32_32x32x16_bf16 v[64:79], v[128:131], v[232:235], v[64:79]
	ds_read_b64_tr_b16 v[228:229], v152 offset:0x2000
	ds_read_b64_tr_b16 v[230:231], v152 offset:0x2800
	ds_read_b64_tr_b16 v[232:233], v152 offset:0x3000
	ds_read_b64_tr_b16 v[234:235], v152 offset:0x3800
	s_waitcnt lgkmcnt(4)
	v_mfma_f32_32x32x16_bf16 v[48:63], v[132:135], v[144:147], v[48:63]
	v_mfma_f32_32x32x16_bf16 v[48:63], v[136:139], v[148:151], v[48:63]
	ds_read_b64_tr_b16 v[144:145], v152 offset:0x200
	ds_read_b64_tr_b16 v[146:147], v152 offset:0xa00
	ds_read_b64_tr_b16 v[148:149], v152 offset:0x1200
	ds_read_b64_tr_b16 v[150:151], v152 offset:0x1a00
	s_waitcnt lgkmcnt(4)
	v_mfma_f32_32x32x16_bf16 v[48:63], v[140:143], v[228:231], v[48:63]
	v_mfma_f32_32x32x16_bf16 v[48:63], v[128:131], v[232:235], v[48:63]
	ds_read_b64_tr_b16 v[228:229], v152 offset:0x2200
	ds_read_b64_tr_b16 v[230:231], v152 offset:0x2a00
	ds_read_b64_tr_b16 v[232:233], v152 offset:0x3200
	ds_read_b64_tr_b16 v[234:235], v152 offset:0x3a00
	s_waitcnt lgkmcnt(4)
	v_mfma_f32_32x32x16_bf16 v[32:47], v[132:135], v[144:147], v[32:47]
	v_mfma_f32_32x32x16_bf16 v[32:47], v[136:139], v[148:151], v[32:47]
	ds_read_b64_tr_b16 v[144:145], v152 offset:0x400
	ds_read_b64_tr_b16 v[146:147], v152 offset:0xc00
	ds_read_b64_tr_b16 v[148:149], v152 offset:0x1400
	ds_read_b64_tr_b16 v[150:151], v152 offset:0x1c00
	s_waitcnt lgkmcnt(4)
	v_mfma_f32_32x32x16_bf16 v[32:47], v[140:143], v[228:231], v[32:47]
	v_mfma_f32_32x32x16_bf16 v[32:47], v[128:131], v[232:235], v[32:47]
	ds_read_b64_tr_b16 v[228:229], v152 offset:0x2400
	ds_read_b64_tr_b16 v[230:231], v152 offset:0x2c00
	ds_read_b64_tr_b16 v[232:233], v152 offset:0x3400
	ds_read_b64_tr_b16 v[234:235], v152 offset:0x3c00
	s_waitcnt lgkmcnt(4)
	v_mfma_f32_32x32x16_bf16 v[16:31], v[132:135], v[144:147], v[16:31]
	v_mfma_f32_32x32x16_bf16 v[16:31], v[136:139], v[148:151], v[16:31]
	ds_read_b64_tr_b16 v[144:145], v152 offset:0x600
	ds_read_b64_tr_b16 v[146:147], v152 offset:0xe00
	ds_read_b64_tr_b16 v[148:149], v152 offset:0x1600
	ds_read_b64_tr_b16 v[150:151], v152 offset:0x1e00
	s_waitcnt lgkmcnt(4)
	v_mfma_f32_32x32x16_bf16 v[16:31], v[140:143], v[228:231], v[16:31]
	v_mfma_f32_32x32x16_bf16 v[16:31], v[128:131], v[232:235], v[16:31]
	ds_read_b64_tr_b16 v[228:229], v152 offset:0x2600
	ds_read_b64_tr_b16 v[230:231], v152 offset:0x2e00
	ds_read_b64_tr_b16 v[232:233], v152 offset:0x3600
	ds_read_b64_tr_b16 v[234:235], v152 offset:0x3e00
	s_waitcnt lgkmcnt(4)
	v_mfma_f32_32x32x16_bf16 v[0:15], v[132:135], v[144:147], v[0:15]
	v_mfma_f32_32x32x16_bf16 v[0:15], v[136:139], v[148:151], v[0:15]
	s_waitcnt lgkmcnt(0)
	v_mfma_f32_32x32x16_bf16 v[0:15], v[140:143], v[228:231], v[0:15]
	v_mfma_f32_32x32x16_bf16 v[0:15], v[128:131], v[232:235], v[0:15]
	s_addk_i32 s37, 0x100
	s_add_i32 s57, s57, 64
	s_waitcnt vmcnt(0) lgkmcnt(0)
	s_barrier
	s_add_u32 s39, s39, 0x80000
	s_addc_u32 s40, s40, 0
	s_add_i32 s36, s36, 1
	v_subrev_u32_e32 v219, 64, v219
	s_cmp_eq_u32 s7, s37
	s_cbranch_scc1 .LBB0_1062

; template <int MODE> __device__ __forceinline__ void partialW2(f32x16& p0, f32x16& p1, const float* auxk, bool band, int qrel, int hi) {
; #pragma unroll
;   for (int g = 0; g < 4; ++g) { const f32x4 a = *(const f32x4*)(auxk + 8 * g + 4 * hi), b = *(const f32x4*)(auxk + 32 + 8 * g + 4 * hi);
; #pragma unroll
;     for (int e = 0; e < 4; ++e) { p0[4 * g + e] *= a[e]; p1[4 * g + e] *= b[e]; } }
;   if (band) {
; #pragma unroll
;     for (int r = 0; r < 16; ++r) { const int kvl = (r & 3) + 8 * (r >> 2);
;       const bool k0 = (MODE == 2) ? (kvl <= qrel) : (kvl >= qrel), k1 = (MODE == 2) ? (kvl + 32 <= qrel) : (kvl + 32 >= qrel);
;       p0[r] = k0 ? p0[r] : 0.f; p1[r] = k1 ? p1[r] : 0.f; }
;   }
; }
; template <int DQK> __device__ __forceinline__ void qkt_acc(f32x16& p0, f32x16& p1, const char* Ks, const bf16x8* qr, int r32, int hi) {
;   constexpr int ROWB = DQK * 2;
;   const int sw = (r32 & 7) << 4; const char* k0p = Ks + r32 * ROWB; const char* k1p = Ks + (32 + r32) * ROWB;
; #pragma unroll
;   for (int d0 = 0; d0 < DQK / 16; ++d0) { const int cb = ((d0 * 16 + hi * 8) * 2) ^ sw;
;     const bf16x8 b0 = *reinterpret_cast<const bf16x8*>(k0p + cb);
;     const bf16x8 b1 = *reinterpret_cast<const bf16x8*>(k1p + cb);
;     p0 = __builtin_amdgcn_mfma_f32_32x32x16_bf16(b0, qr[d0], p0, 0, 0, 0);
;     p1 = __builtin_amdgcn_mfma_f32_32x32x16_bf16(b1, qr[d0], p1, 0, 0, 0); }
; }
.LBB0_1060:
	v_add_u32_e32 v192, s60, v207
	v_add_u32_e32 v200, v192, v208
	ds_read_b128 v[196:199], v200
	ds_read_b128 v[228:231], v200 offset:8192
	v_add_u32_e32 v200, v192, v210
	ds_read_b128 v[232:235], v200
	ds_read_b128 v[244:247], v200 offset:8192
	s_waitcnt lgkmcnt(2)
	v_mfma_f32_32x32x16_bf16 v[128:143], v[196:199], v[160:163], 0
	v_mfma_f32_32x32x16_bf16 v[144:159], v[228:231], v[160:163], 0
	v_add_u32_e32 v200, v192, v211
	ds_read_b128 v[196:199], v200
	ds_read_b128 v[228:231], v200 offset:8192
	s_waitcnt lgkmcnt(2)
	v_mfma_f32_32x32x16_bf16 v[128:143], v[232:235], v[164:167], v[128:143]
	v_mfma_f32_32x32x16_bf16 v[144:159], v[244:247], v[164:167], v[144:159]
	v_add_u32_e32 v200, v192, v212
	ds_read_b128 v[232:235], v200
	ds_read_b128 v[244:247], v200 offset:8192
	s_waitcnt lgkmcnt(2)
	v_mfma_f32_32x32x16_bf16 v[128:143], v[196:199], v[168:171], v[128:143]
	v_mfma_f32_32x32x16_bf16 v[144:159], v[228:231], v[168:171], v[144:159]
	v_add_u32_e32 v200, v192, v213
	ds_read_b128 v[196:199], v200
	ds_read_b128 v[228:231], v200 offset:8192
	s_waitcnt lgkmcnt(2)
	v_mfma_f32_32x32x16_bf16 v[128:143], v[232:235], v[172:175], v[128:143]
	v_mfma_f32_32x32x16_bf16 v[144:159], v[244:247], v[172:175], v[144:159]
	v_add_u32_e32 v200, v192, v214
	ds_read_b128 v[232:235], v200
	ds_read_b128 v[244:247], v200 offset:8192
	s_waitcnt lgkmcnt(2)
	v_mfma_f32_32x32x16_bf16 v[128:143], v[196:199], v[176:179], v[128:143]
	v_mfma_f32_32x32x16_bf16 v[144:159], v[228:231], v[176:179], v[144:159]
	v_add_u32_e32 v200, v192, v215
	ds_read_b128 v[196:199], v200
	ds_read_b128 v[228:231], v200 offset:8192
	s_waitcnt lgkmcnt(2)
	v_mfma_f32_32x32x16_bf16 v[128:143], v[232:235], v[180:183], v[128:143]
	v_mfma_f32_32x32x16_bf16 v[144:159], v[244:247], v[180:183], v[144:159]
	v_add_u32_e32 v200, v192, v216
	ds_read_b128 v[232:235], v200
	ds_read_b128 v[244:247], v200 offset:8192
	s_waitcnt lgkmcnt(2)
	v_mfma_f32_32x32x16_bf16 v[128:143], v[196:199], v[184:187], v[128:143]
	v_mfma_f32_32x32x16_bf16 v[144:159], v[228:231], v[184:187], v[144:159]
	s_waitcnt lgkmcnt(0)
	v_mfma_f32_32x32x16_bf16 v[128:143], v[232:235], v[188:191], v[128:143]
	v_mfma_f32_32x32x16_bf16 v[144:159], v[244:247], v[188:191], v[144:159]
	s_nop 1
	v_add_u32_e32 v192, s37, v218
	v_add_u32_e32 v196, 0x18c00, v192
	v_add_u32_e32 v200, 0x18c80, v192
	ds_read_b128 v[196:199], v196
	ds_read_b128 v[220:223], v200
	s_cmp_le_u32 s57, s67
	s_waitcnt lgkmcnt(1)
	s_nop 1
	v_pk_mul_f32 v[196:197], v[128:129], v[196:197]
	s_waitcnt lgkmcnt(0)
	s_nop 0
	v_pk_mul_f32 v[128:129], v[144:145], v[220:221]
	v_pk_mul_f32 v[144:145], v[130:131], v[198:199]
	v_pk_mul_f32 v[130:131], v[146:147], v[222:223]
	v_add_u32_e32 v146, 0x18c20, v192
	ds_read_b128 v[198:201], v146
	v_add_u32_e32 v146, 0x18ca0, v192
	ds_read_b128 v[220:223], v146
	s_waitcnt lgkmcnt(1)
	v_pk_mul_f32 v[198:199], v[132:133], v[198:199]
	v_add_u32_e32 v132, 0x18c40, v192
	v_pk_mul_f32 v[200:201], v[134:135], v[200:201]
	ds_read_b128 v[132:135], v132
	s_waitcnt lgkmcnt(1)
	v_pk_mul_f32 v[146:147], v[148:149], v[220:221]
	v_pk_mul_f32 v[148:149], v[150:151], v[222:223]
	v_add_u32_e32 v150, 0x18cc0, v192
	ds_read_b128 v[220:223], v150
	s_waitcnt lgkmcnt(1)
	v_pk_mul_f32 v[136:137], v[136:137], v[132:133]
	v_add_u32_e32 v132, 0x18c60, v192
	v_pk_mul_f32 v[138:139], v[138:139], v[134:135]
	ds_read_b128 v[132:135], v132
	s_waitcnt lgkmcnt(1)
	v_pk_mul_f32 v[150:151], v[152:153], v[220:221]
	v_pk_mul_f32 v[152:153], v[154:155], v[222:223]
	v_add_u32_e32 v154, 0x18ce0, v192
	ds_read_b128 v[220:223], v154
	s_waitcnt lgkmcnt(1)
	v_pk_mul_f32 v[140:141], v[140:141], v[132:133]
	v_pk_mul_f32 v[142:143], v[142:143], v[134:135]
	s_waitcnt lgkmcnt(0)
	v_pk_mul_f32 v[154:155], v[156:157], v[220:221]
	v_pk_mul_f32 v[156:157], v[158:159], v[222:223]
	s_cbranch_scc1 .LBB0_1055
	v_cmp_lt_i32_e32 vcc, -1, v219
	s_nop 1
	v_cndmask_b32_e32 v196, 0, v196, vcc
	v_cmp_lt_i32_e32 vcc, 0, v219
	s_nop 1
	v_cndmask_b32_e32 v197, 0, v197, vcc
	v_cmp_lt_i32_e32 vcc, 1, v219
	s_nop 1
	v_cndmask_b32_e32 v144, 0, v144, vcc
	v_cmp_lt_i32_e32 vcc, 2, v219
	s_nop 1
	v_cndmask_b32_e32 v145, 0, v145, vcc
	v_cmp_lt_i32_e32 vcc, 7, v219
	s_nop 1
	v_cndmask_b32_e32 v198, 0, v198, vcc
	v_cmp_lt_i32_e32 vcc, 8, v219
	s_nop 1
	v_cndmask_b32_e32 v199, 0, v199, vcc
	v_cmp_lt_i32_e32 vcc, 9, v219
	s_nop 1
	v_cndmask_b32_e32 v200, 0, v200, vcc
	v_cmp_lt_i32_e32 vcc, 10, v219
	s_nop 1
	v_cndmask_b32_e32 v201, 0, v201, vcc
	v_cmp_lt_i32_e32 vcc, 15, v219
	s_nop 1
	v_cndmask_b32_e32 v136, 0, v136, vcc
	v_cmp_lt_i32_e32 vcc, 16, v219
	s_nop 1
	v_cndmask_b32_e32 v137, 0, v137, vcc
	v_cmp_lt_i32_e32 vcc, 17, v219
	s_nop 1
	v_cndmask_b32_e32 v138, 0, v138, vcc
	v_cmp_lt_i32_e32 vcc, 18, v219
	s_nop 1
	v_cndmask_b32_e32 v139, 0, v139, vcc
	v_cmp_lt_i32_e32 vcc, 23, v219
	s_nop 1
	v_cndmask_b32_e32 v140, 0, v140, vcc
	v_cmp_lt_i32_e32 vcc, 24, v219
	s_nop 1
	v_cndmask_b32_e32 v141, 0, v141, vcc
	v_cmp_lt_i32_e32 vcc, 25, v219
	s_nop 1
	v_cndmask_b32_e32 v142, 0, v142, vcc
	v_cmp_lt_i32_e32 vcc, 26, v219
	s_nop 1
	v_cndmask_b32_e32 v143, 0, v143, vcc
	v_cmp_lt_i32_e32 vcc, 31, v219
	s_nop 1
	v_cndmask_b32_e32 v128, 0, v128, vcc
	v_cmp_lt_i32_e32 vcc, 32, v219
	s_nop 1
	v_cndmask_b32_e32 v129, 0, v129, vcc
	v_cmp_lt_i32_e32 vcc, 33, v219
	s_nop 1
	v_cndmask_b32_e32 v130, 0, v130, vcc
	v_cmp_lt_i32_e32 vcc, 34, v219
	s_nop 1
	v_cndmask_b32_e32 v131, 0, v131, vcc
	v_cmp_lt_i32_e32 vcc, 39, v219
	s_nop 1
	v_cndmask_b32_e32 v146, 0, v146, vcc
	v_cmp_lt_i32_e32 vcc, 40, v219
	s_nop 1
	v_cndmask_b32_e32 v147, 0, v147, vcc
	v_cmp_lt_i32_e32 vcc, 41, v219
	s_nop 1
	v_cndmask_b32_e32 v148, 0, v148, vcc
	v_cmp_lt_i32_e32 vcc, 42, v219
	s_nop 1
	v_cndmask_b32_e32 v149, 0, v149, vcc
	v_cmp_lt_i32_e32 vcc, 47, v219
	s_nop 1
	v_cndmask_b32_e32 v150, 0, v150, vcc
	v_cmp_lt_i32_e32 vcc, 48, v219
	s_nop 1
	v_cndmask_b32_e32 v151, 0, v151, vcc
	v_cmp_lt_i32_e32 vcc, 49, v219
	s_nop 1
	v_cndmask_b32_e32 v152, 0, v152, vcc
	v_cmp_lt_i32_e32 vcc, 50, v219
	s_nop 1
	v_cndmask_b32_e32 v153, 0, v153, vcc
	v_cmp_lt_i32_e32 vcc, 55, v219
	s_nop 1
	v_cndmask_b32_e32 v154, 0, v154, vcc
	v_cmp_lt_i32_e32 vcc, 56, v219
	s_nop 1
	v_cndmask_b32_e32 v155, 0, v155, vcc
	v_cmp_lt_i32_e32 vcc, 57, v219
	s_nop 1
	v_cndmask_b32_e32 v156, 0, v156, vcc
	v_cmp_lt_i32_e32 vcc, 58, v219
	s_nop 1
	v_cndmask_b32_e32 v157, 0, v157, vcc
	s_branch .LBB0_1055

; __device__ __forceinline__ u32x4 pack8(const f32x4 a, const f32x4 b) { u32x4 w; w.x = cvt_pk_bf16(a[0], a[1]); w.y = cvt_pk_bf16(a[2], a[3]); w.z = cvt_pk_bf16(b[0], b[1]); w.w = cvt_pk_bf16(b[2], b[3]); return w; }
; __device__ __forceinline__ float rstd_of(ssq_t ss, float inv_n) { return __builtin_amdgcn_rsqf((float)ss * (1.0f / 16777216.0f) * inv_n + 1e-6f); }
;     __device__ __forceinline__ void operator()(const f32x4 (&acc)[2][2][4][2], const Unit& u, int wr, int wc, int fr, int fq) const {
;         const int row0 = u.pm * BM + wr * 64 + fr, col0 = u.pn * BM + wc * 32 + 8 * fq;
; #pragma unroll
;         for (int ai = 0; ai < 2; ++ai)
; #pragma unroll
;             for (int m = 0; m < 4; ++m) { const int row = row0 + ai * HALF + m * 16; const float rs = rstd_of(ss[row], inv_n);
; #pragma unroll
;                 for (int bj = 0; bj < 2; ++bj) *(u32x4*)(O + (size_t)row * ldc + col0 + bj * HALF) = pack8(acc[ai][bj][m][0] * rs, acc[ai][bj][m][1] * rs); }
;     }
.LBB0_1737:
	v_lshl_add_u32 v144, s56, 8, v152
	v_ashrrev_i32_e32 v145, 31, v144
	v_lshl_add_u64 v[150:151], v[144:145], 3, s[4:5]
	global_load_dwordx2 v[148:149], v[150:151], off
	global_load_dwordx2 v[170:171], v[150:151], off offset:128
	global_load_dwordx2 v[172:173], v[150:151], off offset:256
	global_load_dwordx2 v[174:175], v[150:151], off offset:384
	global_load_dwordx2 v[176:177], v[150:151], off offset:1024
	global_load_dwordx2 v[178:179], v[150:151], off offset:1152
	global_load_dwordx2 v[180:181], v[150:151], off offset:1280
	global_load_dwordx2 v[182:183], v[150:151], off offset:1408
	v_lshl_add_u32 v160, s69, 8, v154
	v_ashrrev_i32_e32 v161, 31, v160
	v_mov_b64_e32 v[146:147], s[44:45]
	v_mad_i64_i32 v[162:163], s[58:59], v144, s68, v[146:147]
	v_or_b32_e32 v164, 16, v144
	v_ashrrev_i32_e32 v165, 31, v164
	v_lshl_add_u64 v[166:167], v[164:165], 3, s[4:5]
	s_andn2_b64 vcc, exec, s[2:3]
	s_mov_b64 s[2:3], -1
	s_waitcnt vmcnt(0)
	v_ffbh_u32_e32 v145, v149
	v_min_u32_e32 v145, 32, v145
	v_lshlrev_b64 v[148:149], v145, v[148:149]
	v_min_u32_e32 v148, 1, v148
	v_or_b32_e32 v148, v149, v148
	v_cvt_f32_u32_e32 v159, v148
	v_sub_u32_e32 v145, 32, v145
	v_lshlrev_b64 v[148:149], 1, v[160:161]
	v_lshl_add_u64 v[162:163], v[162:163], 0, v[148:149]
	v_ldexp_f32 v145, v159, v145
	v_mul_f32_e32 v145, 0x33800000, v145
	v_fmamk_f32 v145, v145, 0x3a000000, v158
	v_rsq_f32_e32 v160, v145
	s_nop 0
	v_pk_mul_f32 v[126:127], v[126:127], v[160:161] op_sel_hi:[1,0]
	v_pk_mul_f32 v[124:125], v[124:125], v[160:161] op_sel_hi:[1,0]
	v_pk_mul_f32 v[122:123], v[122:123], v[160:161] op_sel_hi:[1,0]
	v_pk_mul_f32 v[120:121], v[120:121], v[160:161] op_sel_hi:[1,0]
	v_pk_mul_f32 v[118:119], v[118:119], v[160:161] op_sel_hi:[1,0]
	v_pk_mul_f32 v[116:117], v[116:117], v[160:161] op_sel_hi:[1,0]
	v_pk_mul_f32 v[168:169], v[114:115], v[160:161] op_sel_hi:[1,0]
	v_pk_mul_f32 v[160:161], v[112:113], v[160:161] op_sel_hi:[1,0]
	v_cvt_pk_bf16_f32 v112, v124, v125
	v_cvt_pk_bf16_f32 v113, v126, v127
	v_cvt_pk_bf16_f32 v114, v120, v121
	v_cvt_pk_bf16_f32 v115, v122, v123
	v_cvt_pk_bf16_f32 v116, v116, v117
	v_cvt_pk_bf16_f32 v117, v118, v119
	v_cvt_pk_bf16_f32 v118, v160, v161
	v_cvt_pk_bf16_f32 v119, v168, v169
	global_store_dwordx4 v[162:163], v[112:115], off
	global_store_dwordx4 v[162:163], v[116:119], off offset:256
	s_nop 1
	v_or_b32_e32 v114, 32, v144
	v_ffbh_u32_e32 v115, v171
	v_min_u32_e32 v115, 32, v115
	v_lshlrev_b64 v[112:113], v115, v[170:171]
	v_min_u32_e32 v112, 1, v112
	v_or_b32_e32 v112, v113, v112
	v_cvt_f32_u32_e32 v116, v112
	v_sub_u32_e32 v115, 32, v115
	v_mad_i64_i32 v[112:113], s[58:59], v164, s68, v[146:147]
	v_ldexp_f32 v115, v116, v115
	v_mul_f32_e32 v115, 0x33800000, v115
	v_fmamk_f32 v115, v115, 0x3a000000, v158
	v_rsq_f32_e32 v116, v115
	v_ashrrev_i32_e32 v115, 31, v114
	v_lshl_add_u64 v[112:113], v[112:113], 0, v[148:149]
	v_lshl_add_u64 v[118:119], v[114:115], 3, s[4:5]
	v_pk_mul_f32 v[110:111], v[110:111], v[116:117] op_sel_hi:[1,0]
	v_pk_mul_f32 v[108:109], v[108:109], v[116:117] op_sel_hi:[1,0]
	v_pk_mul_f32 v[106:107], v[106:107], v[116:117] op_sel_hi:[1,0]
	v_pk_mul_f32 v[104:105], v[104:105], v[116:117] op_sel_hi:[1,0]
	v_pk_mul_f32 v[102:103], v[102:103], v[116:117] op_sel_hi:[1,0]
	v_pk_mul_f32 v[100:101], v[100:101], v[116:117] op_sel_hi:[1,0]
	v_pk_mul_f32 v[120:121], v[98:99], v[116:117] op_sel_hi:[1,0]
	v_pk_mul_f32 v[116:117], v[96:97], v[116:117] op_sel_hi:[1,0]
	v_cvt_pk_bf16_f32 v96, v108, v109
	v_cvt_pk_bf16_f32 v97, v110, v111
	v_cvt_pk_bf16_f32 v98, v104, v105
	v_cvt_pk_bf16_f32 v99, v106, v107
	v_cvt_pk_bf16_f32 v100, v100, v101
	v_cvt_pk_bf16_f32 v101, v102, v103
	v_cvt_pk_bf16_f32 v102, v116, v117
	v_cvt_pk_bf16_f32 v103, v120, v121
	global_store_dwordx4 v[112:113], v[96:99], off
	global_store_dwordx4 v[112:113], v[100:103], off offset:256
	s_nop 1
	v_or_b32_e32 v98, 48, v144
	v_ffbh_u32_e32 v99, v173
	v_min_u32_e32 v99, 32, v99
	v_lshlrev_b64 v[96:97], v99, v[172:173]
	v_min_u32_e32 v96, 1, v96
	v_or_b32_e32 v96, v97, v96
	v_cvt_f32_u32_e32 v100, v96
	v_sub_u32_e32 v99, 32, v99
	v_mad_i64_i32 v[96:97], s[58:59], v114, s68, v[146:147]
	v_ldexp_f32 v99, v100, v99
	v_mul_f32_e32 v99, 0x33800000, v99
	v_fmamk_f32 v99, v99, 0x3a000000, v158
	v_rsq_f32_e32 v100, v99
	v_ashrrev_i32_e32 v99, 31, v98
	v_lshl_add_u64 v[96:97], v[96:97], 0, v[148:149]
	v_lshl_add_u64 v[102:103], v[98:99], 3, s[4:5]
	v_pk_mul_f32 v[94:95], v[94:95], v[100:101] op_sel_hi:[1,0]
	v_pk_mul_f32 v[92:93], v[92:93], v[100:101] op_sel_hi:[1,0]
	v_pk_mul_f32 v[90:91], v[90:91], v[100:101] op_sel_hi:[1,0]
	v_pk_mul_f32 v[88:89], v[88:89], v[100:101] op_sel_hi:[1,0]
	v_pk_mul_f32 v[86:87], v[86:87], v[100:101] op_sel_hi:[1,0]
	v_pk_mul_f32 v[84:85], v[84:85], v[100:101] op_sel_hi:[1,0]
	v_pk_mul_f32 v[104:105], v[82:83], v[100:101] op_sel_hi:[1,0]
	v_pk_mul_f32 v[100:101], v[80:81], v[100:101] op_sel_hi:[1,0]
	v_cvt_pk_bf16_f32 v80, v92, v93
	v_cvt_pk_bf16_f32 v81, v94, v95
	v_cvt_pk_bf16_f32 v82, v88, v89
	v_cvt_pk_bf16_f32 v83, v90, v91
	v_cvt_pk_bf16_f32 v84, v84, v85
	v_cvt_pk_bf16_f32 v85, v86, v87
	v_cvt_pk_bf16_f32 v86, v100, v101
	v_cvt_pk_bf16_f32 v87, v104, v105
	global_store_dwordx4 v[96:97], v[80:83], off
	global_store_dwordx4 v[96:97], v[84:87], off offset:256
	s_nop 1
	v_ffbh_u32_e32 v82, v175
	v_min_u32_e32 v82, 32, v82
	v_lshlrev_b64 v[80:81], v82, v[174:175]
	v_min_u32_e32 v80, 1, v80
	v_or_b32_e32 v80, v81, v80
	v_cvt_f32_u32_e32 v80, v80
	v_sub_u32_e32 v81, 32, v82
	v_mad_i64_i32 v[82:83], s[58:59], v98, s68, v[146:147]
	v_ldexp_f32 v80, v80, v81
	v_mul_f32_e32 v80, 0x33800000, v80
	v_fmamk_f32 v80, v80, 0x3a000000, v158
; __device__ __forceinline__ u32x4 pack8(const f32x4 a, const f32x4 b) { u32x4 w; w.x = cvt_pk_bf16(a[0], a[1]); w.y = cvt_pk_bf16(a[2], a[3]); w.z = cvt_pk_bf16(b[0], b[1]); w.w = cvt_pk_bf16(b[2], b[3]); return w; }
; __device__ __forceinline__ float rstd_of(ssq_t ss, float inv_n) { return __builtin_amdgcn_rsqf((float)ss * (1.0f / 16777216.0f) * inv_n + 1e-6f); }
;     __device__ __forceinline__ void operator()(const f32x4 (&acc)[2][2][4][2], const Unit& u, int wr, int wc, int fr, int fq) const {
;         const int row0 = u.pm * BM + wr * 64 + fr, col0 = u.pn * BM + wc * 32 + 8 * fq;
; #pragma unroll
;         for (int ai = 0; ai < 2; ++ai)
; #pragma unroll
;             for (int m = 0; m < 4; ++m) { const int row = row0 + ai * HALF + m * 16; const float rs = rstd_of(ss[row], inv_n);
; #pragma unroll
;                 for (int bj = 0; bj < 2; ++bj) *(u32x4*)(O + (size_t)row * ldc + col0 + bj * HALF) = pack8(acc[ai][bj][m][0] * rs, acc[ai][bj][m][1] * rs); }
;     }
	v_rsq_f32_e32 v80, v80
	v_lshl_add_u64 v[82:83], v[82:83], 0, v[148:149]
	v_pk_mul_f32 v[78:79], v[78:79], v[80:81] op_sel_hi:[1,0]
	v_pk_mul_f32 v[76:77], v[76:77], v[80:81] op_sel_hi:[1,0]
	v_pk_mul_f32 v[74:75], v[74:75], v[80:81] op_sel_hi:[1,0]
	v_pk_mul_f32 v[72:73], v[72:73], v[80:81] op_sel_hi:[1,0]
	v_pk_mul_f32 v[70:71], v[70:71], v[80:81] op_sel_hi:[1,0]
	v_pk_mul_f32 v[68:69], v[68:69], v[80:81] op_sel_hi:[1,0]
	v_pk_mul_f32 v[84:85], v[66:67], v[80:81] op_sel_hi:[1,0]
	v_pk_mul_f32 v[80:81], v[64:65], v[80:81] op_sel_hi:[1,0]
	v_cvt_pk_bf16_f32 v64, v76, v77
	v_cvt_pk_bf16_f32 v65, v78, v79
	v_cvt_pk_bf16_f32 v66, v72, v73
	v_cvt_pk_bf16_f32 v67, v74, v75
	v_cvt_pk_bf16_f32 v68, v68, v69
	v_cvt_pk_bf16_f32 v69, v70, v71
	v_cvt_pk_bf16_f32 v70, v80, v81
	v_cvt_pk_bf16_f32 v71, v84, v85
	global_store_dwordx4 v[82:83], v[64:67], off
	global_store_dwordx4 v[82:83], v[68:71], off offset:256
	s_nop 1
	v_ffbh_u32_e32 v66, v177
	v_min_u32_e32 v66, 32, v66
	v_lshlrev_b64 v[64:65], v66, v[176:177]
	v_min_u32_e32 v64, 1, v64
	v_or_b32_e32 v64, v65, v64
	v_cvt_f32_u32_e32 v64, v64
	v_sub_u32_e32 v66, 32, v66
	v_add_u32_e32 v65, 0x80, v144
	v_ldexp_f32 v64, v64, v66
	v_mul_f32_e32 v64, 0x33800000, v64
	v_fmamk_f32 v64, v64, 0x3a000000, v158
	v_rsq_f32_e32 v64, v64
	v_mad_i64_i32 v[66:67], s[58:59], v65, s68, v[146:147]
	v_lshl_add_u64 v[66:67], v[66:67], 0, v[148:149]
	v_pk_mul_f32 v[62:63], v[62:63], v[64:65] op_sel_hi:[1,0]
	v_pk_mul_f32 v[60:61], v[60:61], v[64:65] op_sel_hi:[1,0]
	v_pk_mul_f32 v[58:59], v[58:59], v[64:65] op_sel_hi:[1,0]
	v_pk_mul_f32 v[56:57], v[56:57], v[64:65] op_sel_hi:[1,0]
	v_pk_mul_f32 v[54:55], v[54:55], v[64:65] op_sel_hi:[1,0]
	v_pk_mul_f32 v[52:53], v[52:53], v[64:65] op_sel_hi:[1,0]
	v_pk_mul_f32 v[68:69], v[50:51], v[64:65] op_sel_hi:[1,0]
	v_pk_mul_f32 v[64:65], v[48:49], v[64:65] op_sel_hi:[1,0]
	v_cvt_pk_bf16_f32 v48, v60, v61
	v_cvt_pk_bf16_f32 v49, v62, v63
	v_cvt_pk_bf16_f32 v50, v56, v57
	v_cvt_pk_bf16_f32 v51, v58, v59
	v_cvt_pk_bf16_f32 v52, v52, v53
	v_cvt_pk_bf16_f32 v53, v54, v55
	v_cvt_pk_bf16_f32 v54, v64, v65
	v_cvt_pk_bf16_f32 v55, v68, v69
	global_store_dwordx4 v[66:67], v[48:51], off
	global_store_dwordx4 v[66:67], v[52:55], off offset:256
	s_nop 1
	v_ffbh_u32_e32 v50, v179
	v_min_u32_e32 v50, 32, v50
	v_lshlrev_b64 v[48:49], v50, v[178:179]
	v_min_u32_e32 v48, 1, v48
	v_or_b32_e32 v48, v49, v48
	v_cvt_f32_u32_e32 v48, v48
	v_sub_u32_e32 v50, 32, v50
	v_add_u32_e32 v49, 0x90, v144
	v_ldexp_f32 v48, v48, v50
	v_mul_f32_e32 v48, 0x33800000, v48
	v_fmamk_f32 v48, v48, 0x3a000000, v158
	v_rsq_f32_e32 v48, v48
	v_mad_i64_i32 v[50:51], s[58:59], v49, s68, v[146:147]
	v_lshl_add_u64 v[50:51], v[50:51], 0, v[148:149]
	v_pk_mul_f32 v[46:47], v[46:47], v[48:49] op_sel_hi:[1,0]
	v_pk_mul_f32 v[44:45], v[44:45], v[48:49] op_sel_hi:[1,0]
	v_pk_mul_f32 v[42:43], v[42:43], v[48:49] op_sel_hi:[1,0]
	v_pk_mul_f32 v[40:41], v[40:41], v[48:49] op_sel_hi:[1,0]
	v_pk_mul_f32 v[38:39], v[38:39], v[48:49] op_sel_hi:[1,0]
	v_pk_mul_f32 v[36:37], v[36:37], v[48:49] op_sel_hi:[1,0]
	v_pk_mul_f32 v[52:53], v[34:35], v[48:49] op_sel_hi:[1,0]
	v_pk_mul_f32 v[48:49], v[32:33], v[48:49] op_sel_hi:[1,0]
	v_cvt_pk_bf16_f32 v32, v44, v45
	v_cvt_pk_bf16_f32 v33, v46, v47
	v_cvt_pk_bf16_f32 v34, v40, v41
	v_cvt_pk_bf16_f32 v35, v42, v43
	v_cvt_pk_bf16_f32 v36, v36, v37
	v_cvt_pk_bf16_f32 v37, v38, v39
	v_cvt_pk_bf16_f32 v38, v48, v49
	v_cvt_pk_bf16_f32 v39, v52, v53
	global_store_dwordx4 v[50:51], v[32:35], off
	global_store_dwordx4 v[50:51], v[36:39], off offset:256
	s_nop 1
	v_ffbh_u32_e32 v34, v181
	v_min_u32_e32 v34, 32, v34
	v_lshlrev_b64 v[32:33], v34, v[180:181]
	v_min_u32_e32 v32, 1, v32
	v_or_b32_e32 v32, v33, v32
	v_cvt_f32_u32_e32 v32, v32
	v_sub_u32_e32 v34, 32, v34
	v_add_u32_e32 v33, 0xa0, v144
	v_ldexp_f32 v32, v32, v34
	v_mul_f32_e32 v32, 0x33800000, v32
	v_fmamk_f32 v32, v32, 0x3a000000, v158
	v_rsq_f32_e32 v32, v32
	v_mad_i64_i32 v[34:35], s[58:59], v33, s68, v[146:147]
	v_lshl_add_u64 v[34:35], v[34:35], 0, v[148:149]
	v_pk_mul_f32 v[30:31], v[30:31], v[32:33] op_sel_hi:[1,0]
	v_pk_mul_f32 v[28:29], v[28:29], v[32:33] op_sel_hi:[1,0]
	v_pk_mul_f32 v[26:27], v[26:27], v[32:33] op_sel_hi:[1,0]
	v_pk_mul_f32 v[24:25], v[24:25], v[32:33] op_sel_hi:[1,0]
	v_pk_mul_f32 v[22:23], v[22:23], v[32:33] op_sel_hi:[1,0]
	v_pk_mul_f32 v[20:21], v[20:21], v[32:33] op_sel_hi:[1,0]
	v_pk_mul_f32 v[36:37], v[18:19], v[32:33] op_sel_hi:[1,0]
	v_pk_mul_f32 v[32:33], v[16:17], v[32:33] op_sel_hi:[1,0]
	v_cvt_pk_bf16_f32 v16, v28, v29
	v_cvt_pk_bf16_f32 v17, v30, v31
	v_cvt_pk_bf16_f32 v18, v24, v25
	v_cvt_pk_bf16_f32 v19, v26, v27
	v_cvt_pk_bf16_f32 v20, v20, v21
	v_cvt_pk_bf16_f32 v21, v22, v23
	v_cvt_pk_bf16_f32 v22, v32, v33
	v_cvt_pk_bf16_f32 v23, v36, v37
	global_store_dwordx4 v[34:35], v[16:19], off
	global_store_dwordx4 v[34:35], v[20:23], off offset:256
	s_nop 1
	v_ffbh_u32_e32 v18, v183
	v_min_u32_e32 v18, 32, v18
	v_lshlrev_b64 v[16:17], v18, v[182:183]
	v_min_u32_e32 v16, 1, v16
	v_or_b32_e32 v16, v17, v16
	v_cvt_f32_u32_e32 v16, v16
	v_sub_u32_e32 v18, 32, v18
	v_add_u32_e32 v17, 0xb0, v144
	v_ldexp_f32 v16, v16, v18
	v_mul_f32_e32 v16, 0x33800000, v16
	v_fmamk_f32 v16, v16, 0x3a000000, v158
	v_rsq_f32_e32 v16, v16
	v_mad_i64_i32 v[18:19], s[58:59], v17, s68, v[146:147]
	v_lshl_add_u64 v[18:19], v[18:19], 0, v[148:149]
	v_pk_mul_f32 v[14:15], v[14:15], v[16:17] op_sel_hi:[1,0]
	v_pk_mul_f32 v[12:13], v[12:13], v[16:17] op_sel_hi:[1,0]
	v_pk_mul_f32 v[10:11], v[10:11], v[16:17] op_sel_hi:[1,0]
	v_pk_mul_f32 v[8:9], v[8:9], v[16:17] op_sel_hi:[1,0]
	v_pk_mul_f32 v[6:7], v[6:7], v[16:17] op_sel_hi:[1,0]
	v_pk_mul_f32 v[4:5], v[4:5], v[16:17] op_sel_hi:[1,0]
	v_pk_mul_f32 v[20:21], v[2:3], v[16:17] op_sel_hi:[1,0]
	v_pk_mul_f32 v[16:17], v[0:1], v[16:17] op_sel_hi:[1,0]
	v_cvt_pk_bf16_f32 v0, v12, v13
	v_cvt_pk_bf16_f32 v1, v14, v15
	v_cvt_pk_bf16_f32 v2, v8, v9
	v_cvt_pk_bf16_f32 v3, v10, v11
	v_cvt_pk_bf16_f32 v4, v4, v5
	v_cvt_pk_bf16_f32 v5, v6, v7
	v_cvt_pk_bf16_f32 v6, v16, v17
	v_cvt_pk_bf16_f32 v7, v20, v21
	global_store_dwordx4 v[18:19], v[0:3], off
	global_store_dwordx4 v[18:19], v[4:7], off offset:256
	s_cbranch_vccnz .LBB0_1730
	s_andn2_b64 vcc, exec, s[0:1]
	s_cbranch_vccnz .LBB0_1729
	s_barrier
	s_branch .LBB0_1729
